# GEMM loops: As[b][0] half-tile staged in SP1(t+1) instead of SP2(t) (DMA pieces per segment 2/4/4/6 instead of 2/6/2/6), SP2 waits vmcnt(6)
# speedup vs baseline: 1.0055x; 1.0032x over previous
.LBB0_152:
	ds_read_b128 v[128:131], v192
	ds_read_b128 v[132:135], v192 offset:1024
	ds_read_b128 v[136:139], v192 offset:2048
	ds_read_b128 v[140:143], v192 offset:3072
	ds_read_b128 v[164:167], v193
	ds_read_b128 v[168:171], v193 offset:1024
	ds_read_b128 v[172:175], v193 offset:2048
	ds_read_b128 v[176:179], v193 offset:3072
	s_add_u32 s78, s70, 0xfffc0080
	s_addc_u32 s79, s71, -1
	s_cmp_eq_u32 s96, 12
	s_cselect_b32 s81, s11, s79
	s_cselect_b32 s80, s22, s78
	s_cselect_b32 s79, s35, s95
	s_cselect_b32 s78, s37, s94
	v_lshl_add_u64 v[228:229], s[70:71], 0, v[156:157]
	s_add_i32 m0, s82, 0xc000
	ds_read_b128 v[196:199], v194
	ds_read_b128 v[200:203], v194 offset:1024
	ds_read_b128 v[204:207], v194 offset:2048
	ds_read_b128 v[208:211], v194 offset:3072
	ds_read_b128 v[212:215], v194 offset:4096
	ds_read_b128 v[216:219], v194 offset:5120
	ds_read_b128 v[220:223], v194 offset:6144
	ds_read_b128 v[224:227], v194 offset:7168
	global_load_lds_dwordx4 v[228:229], off
	v_lshl_add_u64 v[228:229], s[70:71], 0, v[158:159]
	s_add_i32 m0, s82, 0xe000
	s_nop 0
	global_load_lds_dwordx4 v[228:229], off
	s_waitcnt vmcnt(8)
	s_waitcnt lgkmcnt(0)
	s_barrier
	s_waitcnt lgkmcnt(0)
	v_mfma_f32_16x16x32_bf16 v[124:127], v[128:131], v[196:199], v[124:127]
	v_mfma_f32_16x16x32_bf16 v[120:123], v[136:139], v[196:199], v[120:123]
	v_mfma_f32_16x16x32_bf16 v[108:111], v[128:131], v[204:207], v[108:111]
	v_mfma_f32_16x16x32_bf16 v[104:107], v[136:139], v[204:207], v[104:107]
	v_mfma_f32_16x16x32_bf16 v[92:95], v[128:131], v[212:215], v[92:95]
	v_mfma_f32_16x16x32_bf16 v[88:91], v[136:139], v[212:215], v[88:91]
	v_mfma_f32_16x16x32_bf16 v[76:79], v[128:131], v[220:223], v[76:79]
	v_mfma_f32_16x16x32_bf16 v[72:75], v[136:139], v[220:223], v[72:75]
	v_mfma_f32_16x16x32_bf16 v[124:127], v[132:135], v[200:203], v[124:127]
	v_mfma_f32_16x16x32_bf16 v[120:123], v[140:143], v[200:203], v[120:123]
	v_mfma_f32_16x16x32_bf16 v[108:111], v[132:135], v[208:211], v[108:111]
	v_mfma_f32_16x16x32_bf16 v[104:107], v[140:143], v[208:211], v[104:107]
	v_mfma_f32_16x16x32_bf16 v[92:95], v[132:135], v[216:219], v[92:95]
	v_mfma_f32_16x16x32_bf16 v[88:91], v[140:143], v[216:219], v[88:91]
	v_mfma_f32_16x16x32_bf16 v[76:79], v[132:135], v[224:227], v[76:79]
	v_mfma_f32_16x16x32_bf16 v[72:75], v[140:143], v[224:227], v[72:75]
	v_mfma_f32_16x16x32_bf16 v[116:119], v[164:167], v[196:199], v[116:119]
	v_mfma_f32_16x16x32_bf16 v[112:115], v[172:175], v[196:199], v[112:115]
	v_mfma_f32_16x16x32_bf16 v[100:103], v[164:167], v[204:207], v[100:103]
	v_mfma_f32_16x16x32_bf16 v[96:99], v[172:175], v[204:207], v[96:99]
	v_mfma_f32_16x16x32_bf16 v[84:87], v[164:167], v[212:215], v[84:87]
	v_mfma_f32_16x16x32_bf16 v[80:83], v[172:175], v[212:215], v[80:83]
	v_mfma_f32_16x16x32_bf16 v[68:71], v[164:167], v[220:223], v[68:71]
	v_mfma_f32_16x16x32_bf16 v[64:67], v[172:175], v[220:223], v[64:67]
	v_mfma_f32_16x16x32_bf16 v[116:119], v[168:171], v[200:203], v[116:119]
	v_mfma_f32_16x16x32_bf16 v[112:115], v[176:179], v[200:203], v[112:115]
	v_mfma_f32_16x16x32_bf16 v[100:103], v[168:171], v[208:211], v[100:103]
	v_mfma_f32_16x16x32_bf16 v[96:99], v[176:179], v[208:211], v[96:99]
	v_mfma_f32_16x16x32_bf16 v[84:87], v[168:171], v[216:219], v[84:87]
	v_mfma_f32_16x16x32_bf16 v[80:83], v[176:179], v[216:219], v[80:83]
	v_mfma_f32_16x16x32_bf16 v[68:71], v[168:171], v[224:227], v[68:71]
	v_mfma_f32_16x16x32_bf16 v[64:67], v[176:179], v[224:227], v[64:67]
	s_barrier
	s_add_i32 s97, s90, s33
	v_lshl_add_u64 v[228:229], s[78:79], 0, v[146:147]
	s_mov_b32 m0, s97
	ds_read_b128 v[196:199], v194 offset:16384
	ds_read_b128 v[200:203], v194 offset:17408
	ds_read_b128 v[204:207], v194 offset:18432
	ds_read_b128 v[208:211], v194 offset:19456
	ds_read_b128 v[212:215], v194 offset:20480
	ds_read_b128 v[216:219], v194 offset:21504
	ds_read_b128 v[220:223], v194 offset:22528
	ds_read_b128 v[224:227], v194 offset:23552
	global_load_lds_dwordx4 v[228:229], off
	s_add_i32 m0, s97, 0x2000
	s_add_u32 vcc_lo, s78, 0x40000
	v_lshl_add_u64 v[230:231], s[78:79], 0, v[150:151]
	s_addc_u32 vcc_hi, s79, 0
	s_add_i32 s97, s91, s33
	global_load_lds_dwordx4 v[230:231], off
	v_lshl_add_u64 v[232:233], vcc, 0, v[146:147]
	s_mov_b32 m0, s97
	global_load_lds_dwordx4 v[232:233], off
	v_lshl_add_u64 v[232:233], vcc, 0, v[150:151]
	s_add_i32 m0, s97, 0x2000
	s_nop 0
	global_load_lds_dwordx4 v[232:233], off
	s_waitcnt vmcnt(6)
	s_waitcnt lgkmcnt(0)
	s_barrier
	s_waitcnt lgkmcnt(0)
	v_mfma_f32_16x16x32_bf16 v[60:63], v[128:131], v[196:199], v[60:63]
	v_mfma_f32_16x16x32_bf16 v[56:59], v[136:139], v[196:199], v[56:59]
	v_mfma_f32_16x16x32_bf16 v[44:47], v[128:131], v[204:207], v[44:47]
	v_mfma_f32_16x16x32_bf16 v[40:43], v[136:139], v[204:207], v[40:43]
	v_mfma_f32_16x16x32_bf16 v[28:31], v[128:131], v[212:215], v[28:31]
	v_mfma_f32_16x16x32_bf16 v[24:27], v[136:139], v[212:215], v[24:27]
	v_mfma_f32_16x16x32_bf16 v[12:15], v[128:131], v[220:223], v[12:15]
	v_mfma_f32_16x16x32_bf16 v[8:11], v[136:139], v[220:223], v[8:11]
	v_mfma_f32_16x16x32_bf16 v[60:63], v[132:135], v[200:203], v[60:63]
	v_mfma_f32_16x16x32_bf16 v[56:59], v[140:143], v[200:203], v[56:59]
	v_mfma_f32_16x16x32_bf16 v[44:47], v[132:135], v[208:211], v[44:47]
	v_mfma_f32_16x16x32_bf16 v[40:43], v[140:143], v[208:211], v[40:43]
	v_mfma_f32_16x16x32_bf16 v[28:31], v[132:135], v[216:219], v[28:31]
	v_mfma_f32_16x16x32_bf16 v[24:27], v[140:143], v[216:219], v[24:27]
	v_mfma_f32_16x16x32_bf16 v[12:15], v[132:135], v[224:227], v[12:15]
	v_mfma_f32_16x16x32_bf16 v[8:11], v[140:143], v[224:227], v[8:11]
	v_mfma_f32_16x16x32_bf16 v[52:55], v[164:167], v[196:199], v[52:55]
	v_mfma_f32_16x16x32_bf16 v[48:51], v[172:175], v[196:199], v[48:51]
	v_mfma_f32_16x16x32_bf16 v[36:39], v[164:167], v[204:207], v[36:39]
	v_mfma_f32_16x16x32_bf16 v[32:35], v[172:175], v[204:207], v[32:35]
	v_mfma_f32_16x16x32_bf16 v[20:23], v[164:167], v[212:215], v[20:23]
	v_mfma_f32_16x16x32_bf16 v[16:19], v[172:175], v[212:215], v[16:19]
	v_mfma_f32_16x16x32_bf16 v[4:7], v[164:167], v[220:223], v[4:7]
	v_mfma_f32_16x16x32_bf16 v[0:3], v[172:175], v[220:223], v[0:3]
	v_mfma_f32_16x16x32_bf16 v[52:55], v[168:171], v[200:203], v[52:55]
	v_mfma_f32_16x16x32_bf16 v[48:51], v[176:179], v[200:203], v[48:51]
	v_mfma_f32_16x16x32_bf16 v[36:39], v[168:171], v[208:211], v[36:39]
	v_mfma_f32_16x16x32_bf16 v[32:35], v[176:179], v[208:211], v[32:35]
	v_mfma_f32_16x16x32_bf16 v[20:23], v[168:171], v[216:219], v[20:23]
	v_mfma_f32_16x16x32_bf16 v[16:19], v[176:179], v[216:219], v[16:19]
	v_mfma_f32_16x16x32_bf16 v[4:7], v[168:171], v[224:227], v[4:7]
	v_mfma_f32_16x16x32_bf16 v[0:3], v[176:179], v[224:227], v[0:3]
	s_barrier
	s_add_i32 s97, 0, 0x18000
	s_add_i32 vcc_lo, 0, 0x1c000
	v_add_u32_e32 v140, s97, v180
	v_add_u32_e32 v152, vcc_lo, v180
	ds_read_b128 v[128:131], v140
	ds_read_b128 v[132:135], v140 offset:1024
	ds_read_b128 v[136:139], v140 offset:2048
	ds_read_b128 v[140:143], v140 offset:3072
	ds_read_b128 v[164:167], v152
	ds_read_b128 v[168:171], v152 offset:1024
	ds_read_b128 v[172:175], v152 offset:2048
	ds_read_b128 v[176:179], v152 offset:3072
	v_lshl_add_u64 v[232:233], s[80:81], 0, v[144:145]
	s_mov_b32 m0, s82
	v_lshl_add_u64 v[234:235], s[80:81], 0, v[148:149]
	global_load_lds_dwordx4 v[232:233], off
	s_mov_b32 m0, s83
	s_nop 0
	global_load_lds_dwordx4 v[234:235], off
	s_add_u32 s80, s80, 0x40000
	s_addc_u32 s81, s81, 0
	s_mov_b32 m0, s84
	v_lshl_add_u64 v[236:237], s[80:81], 0, v[144:145]
	ds_read_b128 v[196:199], v194 offset:32768
	ds_read_b128 v[200:203], v194 offset:33792
	ds_read_b128 v[204:207], v194 offset:34816
	ds_read_b128 v[208:211], v194 offset:35840
	ds_read_b128 v[212:215], v194 offset:36864
	ds_read_b128 v[216:219], v194 offset:37888
	ds_read_b128 v[220:223], v194 offset:38912
	ds_read_b128 v[224:227], v194 offset:39936
	global_load_lds_dwordx4 v[236:237], off
	v_lshl_add_u64 v[236:237], s[80:81], 0, v[148:149]
	s_mov_b32 m0, s85
	s_nop 0
	global_load_lds_dwordx4 v[236:237], off
	s_waitcnt vmcnt(8)
	s_waitcnt lgkmcnt(0)
	s_barrier
	s_waitcnt lgkmcnt(0)
	v_mfma_f32_16x16x32_bf16 v[124:127], v[128:131], v[196:199], v[124:127]
	v_mfma_f32_16x16x32_bf16 v[120:123], v[136:139], v[196:199], v[120:123]
	v_mfma_f32_16x16x32_bf16 v[108:111], v[128:131], v[204:207], v[108:111]
	v_mfma_f32_16x16x32_bf16 v[104:107], v[136:139], v[204:207], v[104:107]
	v_mfma_f32_16x16x32_bf16 v[92:95], v[128:131], v[212:215], v[92:95]
	v_mfma_f32_16x16x32_bf16 v[88:91], v[136:139], v[212:215], v[88:91]
	v_mfma_f32_16x16x32_bf16 v[76:79], v[128:131], v[220:223], v[76:79]
	v_mfma_f32_16x16x32_bf16 v[72:75], v[136:139], v[220:223], v[72:75]
	v_mfma_f32_16x16x32_bf16 v[124:127], v[132:135], v[200:203], v[124:127]
	v_mfma_f32_16x16x32_bf16 v[120:123], v[140:143], v[200:203], v[120:123]
	v_mfma_f32_16x16x32_bf16 v[108:111], v[132:135], v[208:211], v[108:111]
	v_mfma_f32_16x16x32_bf16 v[104:107], v[140:143], v[208:211], v[104:107]
	v_mfma_f32_16x16x32_bf16 v[92:95], v[132:135], v[216:219], v[92:95]
	v_mfma_f32_16x16x32_bf16 v[88:91], v[140:143], v[216:219], v[88:91]
	v_mfma_f32_16x16x32_bf16 v[76:79], v[132:135], v[224:227], v[76:79]
	v_mfma_f32_16x16x32_bf16 v[72:75], v[140:143], v[224:227], v[72:75]
	v_mfma_f32_16x16x32_bf16 v[116:119], v[164:167], v[196:199], v[116:119]
	v_mfma_f32_16x16x32_bf16 v[112:115], v[172:175], v[196:199], v[112:115]
	v_mfma_f32_16x16x32_bf16 v[100:103], v[164:167], v[204:207], v[100:103]
	v_mfma_f32_16x16x32_bf16 v[96:99], v[172:175], v[204:207], v[96:99]
	v_mfma_f32_16x16x32_bf16 v[84:87], v[164:167], v[212:215], v[84:87]
	v_mfma_f32_16x16x32_bf16 v[80:83], v[172:175], v[212:215], v[80:83]
	v_mfma_f32_16x16x32_bf16 v[68:71], v[164:167], v[220:223], v[68:71]
	v_mfma_f32_16x16x32_bf16 v[64:67], v[172:175], v[220:223], v[64:67]
	v_mfma_f32_16x16x32_bf16 v[116:119], v[168:171], v[200:203], v[116:119]
	v_mfma_f32_16x16x32_bf16 v[112:115], v[176:179], v[200:203], v[112:115]
	v_mfma_f32_16x16x32_bf16 v[100:103], v[168:171], v[208:211], v[100:103]
	v_mfma_f32_16x16x32_bf16 v[96:99], v[176:179], v[208:211], v[96:99]
	v_mfma_f32_16x16x32_bf16 v[84:87], v[168:171], v[216:219], v[84:87]
	v_mfma_f32_16x16x32_bf16 v[80:83], v[176:179], v[216:219], v[80:83]
	v_mfma_f32_16x16x32_bf16 v[68:71], v[168:171], v[224:227], v[68:71]
	v_mfma_f32_16x16x32_bf16 v[64:67], v[176:179], v[224:227], v[64:67]
	s_barrier
	s_add_i32 s80, s97, s33
	v_lshl_add_u64 v[228:229], v[228:229], 0, s[26:27]
	s_mov_b32 m0, s80
	ds_read_b128 v[196:199], v194 offset:49152
	ds_read_b128 v[200:203], v194 offset:50176
	ds_read_b128 v[204:207], v194 offset:51200
	ds_read_b128 v[208:211], v194 offset:52224
	ds_read_b128 v[212:215], v194 offset:53248
	ds_read_b128 v[216:219], v194 offset:54272
	ds_read_b128 v[220:223], v194 offset:55296
	ds_read_b128 v[224:227], v194 offset:56320
	global_load_lds_dwordx4 v[228:229], off
	s_add_i32 m0, s80, 0x2000
	s_add_u32 s78, s78, 0x40080
	v_lshl_add_u64 v[228:229], v[230:231], 0, s[26:27]
	s_addc_u32 s79, s79, 0
	s_add_i32 s80, vcc_lo, s33
	global_load_lds_dwordx4 v[228:229], off
	v_lshl_add_u64 v[228:229], s[78:79], 0, v[146:147]
	s_mov_b32 m0, s80
	s_nop 0
	global_load_lds_dwordx4 v[228:229], off
	v_lshl_add_u64 v[228:229], s[78:79], 0, v[150:151]
	s_add_i32 m0, s80, 0x2000
	s_nop 0
	global_load_lds_dwordx4 v[228:229], off
	v_lshl_add_u64 v[228:229], v[232:233], 0, s[26:27]
	s_mov_b32 m0, s87
	s_nop 0
	global_load_lds_dwordx4 v[228:229], off
	v_lshl_add_u64 v[228:229], v[234:235], 0, s[26:27]
	s_mov_b32 m0, s88
	s_nop 0
	global_load_lds_dwordx4 v[228:229], off
	s_waitcnt vmcnt(6)
	s_waitcnt lgkmcnt(0)
	s_barrier
	s_waitcnt lgkmcnt(0)
	v_mfma_f32_16x16x32_bf16 v[60:63], v[128:131], v[196:199], v[60:63]
	v_mfma_f32_16x16x32_bf16 v[56:59], v[136:139], v[196:199], v[56:59]
	v_mfma_f32_16x16x32_bf16 v[44:47], v[128:131], v[204:207], v[44:47]
	v_mfma_f32_16x16x32_bf16 v[40:43], v[136:139], v[204:207], v[40:43]
	v_mfma_f32_16x16x32_bf16 v[28:31], v[128:131], v[212:215], v[28:31]
	v_mfma_f32_16x16x32_bf16 v[24:27], v[136:139], v[212:215], v[24:27]
	v_mfma_f32_16x16x32_bf16 v[12:15], v[128:131], v[220:223], v[12:15]
	v_mfma_f32_16x16x32_bf16 v[8:11], v[136:139], v[220:223], v[8:11]
	v_mfma_f32_16x16x32_bf16 v[60:63], v[132:135], v[200:203], v[60:63]
	v_mfma_f32_16x16x32_bf16 v[56:59], v[140:143], v[200:203], v[56:59]
	v_mfma_f32_16x16x32_bf16 v[44:47], v[132:135], v[208:211], v[44:47]
	v_mfma_f32_16x16x32_bf16 v[40:43], v[140:143], v[208:211], v[40:43]
	v_mfma_f32_16x16x32_bf16 v[28:31], v[132:135], v[216:219], v[28:31]
	v_mfma_f32_16x16x32_bf16 v[24:27], v[140:143], v[216:219], v[24:27]
	v_mfma_f32_16x16x32_bf16 v[12:15], v[132:135], v[224:227], v[12:15]
	v_mfma_f32_16x16x32_bf16 v[8:11], v[140:143], v[224:227], v[8:11]
	v_mfma_f32_16x16x32_bf16 v[52:55], v[164:167], v[196:199], v[52:55]
	v_mfma_f32_16x16x32_bf16 v[48:51], v[172:175], v[196:199], v[48:51]
	v_mfma_f32_16x16x32_bf16 v[36:39], v[164:167], v[204:207], v[36:39]
	v_mfma_f32_16x16x32_bf16 v[32:35], v[172:175], v[204:207], v[32:35]
	v_mfma_f32_16x16x32_bf16 v[20:23], v[164:167], v[212:215], v[20:23]
	v_mfma_f32_16x16x32_bf16 v[16:19], v[172:175], v[212:215], v[16:19]
	v_mfma_f32_16x16x32_bf16 v[4:7], v[164:167], v[220:223], v[4:7]
	v_mfma_f32_16x16x32_bf16 v[0:3], v[172:175], v[220:223], v[0:3]
	v_mfma_f32_16x16x32_bf16 v[52:55], v[168:171], v[200:203], v[52:55]
	v_mfma_f32_16x16x32_bf16 v[48:51], v[176:179], v[200:203], v[48:51]
	v_mfma_f32_16x16x32_bf16 v[36:39], v[168:171], v[208:211], v[36:39]
	v_mfma_f32_16x16x32_bf16 v[32:35], v[176:179], v[208:211], v[32:35]
	v_mfma_f32_16x16x32_bf16 v[20:23], v[168:171], v[216:219], v[20:23]
	v_mfma_f32_16x16x32_bf16 v[16:19], v[176:179], v[216:219], v[16:19]
	v_mfma_f32_16x16x32_bf16 v[4:7], v[168:171], v[224:227], v[4:7]
	v_mfma_f32_16x16x32_bf16 v[0:3], v[176:179], v[224:227], v[0:3]
	s_barrier
	s_add_i32 s96, s96, 2
	s_add_u32 s70, s70, 0x100
	s_addc_u32 s71, s71, 0
	s_add_u32 s94, s94, 0x100
	s_addc_u32 s95, s95, 0
	s_cmp_gt_u32 s96, 13
	s_cbranch_scc0 .LBB0_152
	s_and_b64 vcc, exec, s[28:29]
	s_cbranch_vccz .LBB0_155
	s_barrier

.LBB0_617:
	ds_read_b128 v[144:147], v151
	ds_read_b128 v[156:159], v151 offset:1024
	ds_read_b128 v[160:163], v151 offset:2048
	ds_read_b128 v[164:167], v151 offset:3072
	ds_read_b128 v[168:171], v152
	ds_read_b128 v[172:175], v152 offset:1024
	ds_read_b128 v[176:179], v152 offset:2048
	ds_read_b128 v[184:187], v152 offset:3072
	s_add_u32 s26, s24, 0xfffc0080
	s_addc_u32 s27, s25, -1
	s_cmp_eq_u32 s51, 12
	s_cselect_b32 s29, s17, s27
	s_cselect_b32 s28, s23, s26
	s_cselect_b32 s27, s15, s50
	s_cselect_b32 s26, s46, s47
	v_lshl_add_u64 v[220:221], s[24:25], 0, v[136:137]
	s_add_i32 m0, s34, 0xc000
	ds_read_b128 v[188:191], v153
	ds_read_b128 v[192:195], v153 offset:1024
	ds_read_b128 v[196:199], v153 offset:2048
	ds_read_b128 v[200:203], v153 offset:3072
	ds_read_b128 v[204:207], v153 offset:4096
	ds_read_b128 v[208:211], v153 offset:5120
	ds_read_b128 v[212:215], v153 offset:6144
	ds_read_b128 v[216:219], v153 offset:7168
	global_load_lds_dwordx4 v[220:221], off
	v_lshl_add_u64 v[220:221], s[24:25], 0, v[138:139]
	s_add_i32 m0, s34, 0xe000
	s_nop 0
	global_load_lds_dwordx4 v[220:221], off
	s_waitcnt vmcnt(8)
	s_waitcnt lgkmcnt(0)
	s_barrier
	s_waitcnt lgkmcnt(0)
	v_mfma_f32_16x16x32_bf16 v[124:127], v[144:147], v[188:191], v[124:127]
	v_mfma_f32_16x16x32_bf16 v[120:123], v[160:163], v[188:191], v[120:123]
	v_mfma_f32_16x16x32_bf16 v[108:111], v[144:147], v[196:199], v[108:111]
	v_mfma_f32_16x16x32_bf16 v[104:107], v[160:163], v[196:199], v[104:107]
	v_mfma_f32_16x16x32_bf16 v[92:95], v[144:147], v[204:207], v[92:95]
	v_mfma_f32_16x16x32_bf16 v[88:91], v[160:163], v[204:207], v[88:91]
	v_mfma_f32_16x16x32_bf16 v[76:79], v[144:147], v[212:215], v[76:79]
	v_mfma_f32_16x16x32_bf16 v[72:75], v[160:163], v[212:215], v[72:75]
	v_mfma_f32_16x16x32_bf16 v[124:127], v[156:159], v[192:195], v[124:127]
	v_mfma_f32_16x16x32_bf16 v[120:123], v[164:167], v[192:195], v[120:123]
	v_mfma_f32_16x16x32_bf16 v[108:111], v[156:159], v[200:203], v[108:111]
	v_mfma_f32_16x16x32_bf16 v[104:107], v[164:167], v[200:203], v[104:107]
	v_mfma_f32_16x16x32_bf16 v[92:95], v[156:159], v[208:211], v[92:95]
	v_mfma_f32_16x16x32_bf16 v[88:91], v[164:167], v[208:211], v[88:91]
	v_mfma_f32_16x16x32_bf16 v[76:79], v[156:159], v[216:219], v[76:79]
	v_mfma_f32_16x16x32_bf16 v[72:75], v[164:167], v[216:219], v[72:75]
	v_mfma_f32_16x16x32_bf16 v[116:119], v[168:171], v[188:191], v[116:119]
	v_mfma_f32_16x16x32_bf16 v[112:115], v[176:179], v[188:191], v[112:115]
	v_mfma_f32_16x16x32_bf16 v[100:103], v[168:171], v[196:199], v[100:103]
	v_mfma_f32_16x16x32_bf16 v[96:99], v[176:179], v[196:199], v[96:99]
	v_mfma_f32_16x16x32_bf16 v[84:87], v[168:171], v[204:207], v[84:87]
	v_mfma_f32_16x16x32_bf16 v[80:83], v[176:179], v[204:207], v[80:83]
	v_mfma_f32_16x16x32_bf16 v[68:71], v[168:171], v[212:215], v[68:71]
	v_mfma_f32_16x16x32_bf16 v[64:67], v[176:179], v[212:215], v[64:67]
	v_mfma_f32_16x16x32_bf16 v[116:119], v[172:175], v[192:195], v[116:119]
	v_mfma_f32_16x16x32_bf16 v[112:115], v[184:187], v[192:195], v[112:115]
	v_mfma_f32_16x16x32_bf16 v[100:103], v[172:175], v[200:203], v[100:103]
	v_mfma_f32_16x16x32_bf16 v[96:99], v[184:187], v[200:203], v[96:99]
	v_mfma_f32_16x16x32_bf16 v[84:87], v[172:175], v[208:211], v[84:87]
	v_mfma_f32_16x16x32_bf16 v[80:83], v[184:187], v[208:211], v[80:83]
	v_mfma_f32_16x16x32_bf16 v[68:71], v[172:175], v[216:219], v[68:71]
	v_mfma_f32_16x16x32_bf16 v[64:67], v[184:187], v[216:219], v[64:67]
	s_barrier
	s_add_i32 s52, s41, s33
	v_lshl_add_u64 v[220:221], s[26:27], 0, v[130:131]
	s_mov_b32 m0, s52
	ds_read_b128 v[188:191], v153 offset:16384
	ds_read_b128 v[192:195], v153 offset:17408
	ds_read_b128 v[196:199], v153 offset:18432
	ds_read_b128 v[200:203], v153 offset:19456
	ds_read_b128 v[204:207], v153 offset:20480
	ds_read_b128 v[208:211], v153 offset:21504
	ds_read_b128 v[212:215], v153 offset:22528
	ds_read_b128 v[216:219], v153 offset:23552
	global_load_lds_dwordx4 v[220:221], off
	s_add_i32 m0, s52, 0x2000
	s_add_u32 s52, s26, 0x40000
	v_lshl_add_u64 v[222:223], s[26:27], 0, v[134:135]
	s_addc_u32 s53, s27, 0
	s_add_i32 s54, s42, s33
	global_load_lds_dwordx4 v[222:223], off
	v_lshl_add_u64 v[224:225], s[52:53], 0, v[130:131]
	s_mov_b32 m0, s54
	global_load_lds_dwordx4 v[224:225], off
	v_lshl_add_u64 v[224:225], s[52:53], 0, v[134:135]
	s_add_i32 m0, s54, 0x2000
	s_nop 0
	global_load_lds_dwordx4 v[224:225], off
	s_waitcnt vmcnt(6)
	s_waitcnt lgkmcnt(0)
	s_barrier
	s_waitcnt lgkmcnt(0)
	v_mfma_f32_16x16x32_bf16 v[60:63], v[144:147], v[188:191], v[60:63]
	v_mfma_f32_16x16x32_bf16 v[56:59], v[160:163], v[188:191], v[56:59]
	v_mfma_f32_16x16x32_bf16 v[44:47], v[144:147], v[196:199], v[44:47]
	v_mfma_f32_16x16x32_bf16 v[40:43], v[160:163], v[196:199], v[40:43]
	v_mfma_f32_16x16x32_bf16 v[28:31], v[144:147], v[204:207], v[28:31]
	v_mfma_f32_16x16x32_bf16 v[24:27], v[160:163], v[204:207], v[24:27]
	v_mfma_f32_16x16x32_bf16 v[12:15], v[144:147], v[212:215], v[12:15]
	v_mfma_f32_16x16x32_bf16 v[8:11], v[160:163], v[212:215], v[8:11]
	v_mfma_f32_16x16x32_bf16 v[60:63], v[156:159], v[192:195], v[60:63]
	v_mfma_f32_16x16x32_bf16 v[56:59], v[164:167], v[192:195], v[56:59]
	v_mfma_f32_16x16x32_bf16 v[44:47], v[156:159], v[200:203], v[44:47]
	v_mfma_f32_16x16x32_bf16 v[40:43], v[164:167], v[200:203], v[40:43]
	v_mfma_f32_16x16x32_bf16 v[28:31], v[156:159], v[208:211], v[28:31]
	v_mfma_f32_16x16x32_bf16 v[24:27], v[164:167], v[208:211], v[24:27]
	v_mfma_f32_16x16x32_bf16 v[12:15], v[156:159], v[216:219], v[12:15]
	v_mfma_f32_16x16x32_bf16 v[8:11], v[164:167], v[216:219], v[8:11]
	v_mfma_f32_16x16x32_bf16 v[52:55], v[168:171], v[188:191], v[52:55]
	v_mfma_f32_16x16x32_bf16 v[48:51], v[176:179], v[188:191], v[48:51]
	v_mfma_f32_16x16x32_bf16 v[36:39], v[168:171], v[196:199], v[36:39]
	v_mfma_f32_16x16x32_bf16 v[32:35], v[176:179], v[196:199], v[32:35]
	v_mfma_f32_16x16x32_bf16 v[20:23], v[168:171], v[204:207], v[20:23]
	v_mfma_f32_16x16x32_bf16 v[16:19], v[176:179], v[204:207], v[16:19]
	v_mfma_f32_16x16x32_bf16 v[4:7], v[168:171], v[212:215], v[4:7]
	v_mfma_f32_16x16x32_bf16 v[0:3], v[176:179], v[212:215], v[0:3]
	v_mfma_f32_16x16x32_bf16 v[52:55], v[172:175], v[192:195], v[52:55]
	v_mfma_f32_16x16x32_bf16 v[48:51], v[184:187], v[192:195], v[48:51]
	v_mfma_f32_16x16x32_bf16 v[36:39], v[172:175], v[200:203], v[36:39]
	v_mfma_f32_16x16x32_bf16 v[32:35], v[184:187], v[200:203], v[32:35]
	v_mfma_f32_16x16x32_bf16 v[20:23], v[172:175], v[208:211], v[20:23]
	v_mfma_f32_16x16x32_bf16 v[16:19], v[184:187], v[208:211], v[16:19]
	v_mfma_f32_16x16x32_bf16 v[4:7], v[172:175], v[216:219], v[4:7]
	v_mfma_f32_16x16x32_bf16 v[0:3], v[184:187], v[216:219], v[0:3]
	s_barrier
	s_add_i32 s52, 0, 0x18000
	v_add_u32_e32 v155, s52, v149
	s_add_i32 s53, 0, 0x1c000
	ds_read_b128 v[144:147], v155
	ds_read_b128 v[156:159], v155 offset:1024
	ds_read_b128 v[160:163], v155 offset:2048
	ds_read_b128 v[164:167], v155 offset:3072
	v_add_u32_e32 v155, s53, v149
	ds_read_b128 v[168:171], v155
	ds_read_b128 v[172:175], v155 offset:1024
	ds_read_b128 v[176:179], v155 offset:2048
	ds_read_b128 v[184:187], v155 offset:3072
	v_lshl_add_u64 v[224:225], s[28:29], 0, v[128:129]
	s_mov_b32 m0, s34
	v_lshl_add_u64 v[226:227], s[28:29], 0, v[132:133]
	global_load_lds_dwordx4 v[224:225], off
	s_mov_b32 m0, s35
	s_nop 0
	global_load_lds_dwordx4 v[226:227], off
	s_add_u32 s28, s28, 0x40000
	s_addc_u32 s29, s29, 0
	s_mov_b32 m0, s36
	v_lshl_add_u64 v[228:229], s[28:29], 0, v[128:129]
	ds_read_b128 v[188:191], v153 offset:32768
	ds_read_b128 v[192:195], v153 offset:33792
	ds_read_b128 v[196:199], v153 offset:34816
	ds_read_b128 v[200:203], v153 offset:35840
	ds_read_b128 v[204:207], v153 offset:36864
	ds_read_b128 v[208:211], v153 offset:37888
	ds_read_b128 v[212:215], v153 offset:38912
	ds_read_b128 v[216:219], v153 offset:39936
	global_load_lds_dwordx4 v[228:229], off
	v_lshl_add_u64 v[228:229], s[28:29], 0, v[132:133]
	s_mov_b32 m0, s37
	s_nop 0
	global_load_lds_dwordx4 v[228:229], off
	s_waitcnt vmcnt(8)
	s_waitcnt lgkmcnt(0)
	s_barrier
	s_waitcnt lgkmcnt(0)
	v_mfma_f32_16x16x32_bf16 v[124:127], v[144:147], v[188:191], v[124:127]
	v_mfma_f32_16x16x32_bf16 v[120:123], v[160:163], v[188:191], v[120:123]
	v_mfma_f32_16x16x32_bf16 v[108:111], v[144:147], v[196:199], v[108:111]
	v_mfma_f32_16x16x32_bf16 v[104:107], v[160:163], v[196:199], v[104:107]
	v_mfma_f32_16x16x32_bf16 v[92:95], v[144:147], v[204:207], v[92:95]
	v_mfma_f32_16x16x32_bf16 v[88:91], v[160:163], v[204:207], v[88:91]
	v_mfma_f32_16x16x32_bf16 v[76:79], v[144:147], v[212:215], v[76:79]
	v_mfma_f32_16x16x32_bf16 v[72:75], v[160:163], v[212:215], v[72:75]
	v_mfma_f32_16x16x32_bf16 v[124:127], v[156:159], v[192:195], v[124:127]
	v_mfma_f32_16x16x32_bf16 v[120:123], v[164:167], v[192:195], v[120:123]
	v_mfma_f32_16x16x32_bf16 v[108:111], v[156:159], v[200:203], v[108:111]
	v_mfma_f32_16x16x32_bf16 v[104:107], v[164:167], v[200:203], v[104:107]
	v_mfma_f32_16x16x32_bf16 v[92:95], v[156:159], v[208:211], v[92:95]
	v_mfma_f32_16x16x32_bf16 v[88:91], v[164:167], v[208:211], v[88:91]
	v_mfma_f32_16x16x32_bf16 v[76:79], v[156:159], v[216:219], v[76:79]
	v_mfma_f32_16x16x32_bf16 v[72:75], v[164:167], v[216:219], v[72:75]
	v_mfma_f32_16x16x32_bf16 v[116:119], v[168:171], v[188:191], v[116:119]
	v_mfma_f32_16x16x32_bf16 v[112:115], v[176:179], v[188:191], v[112:115]
	v_mfma_f32_16x16x32_bf16 v[100:103], v[168:171], v[196:199], v[100:103]
	v_mfma_f32_16x16x32_bf16 v[96:99], v[176:179], v[196:199], v[96:99]
	v_mfma_f32_16x16x32_bf16 v[84:87], v[168:171], v[204:207], v[84:87]
	v_mfma_f32_16x16x32_bf16 v[80:83], v[176:179], v[204:207], v[80:83]
	v_mfma_f32_16x16x32_bf16 v[68:71], v[168:171], v[212:215], v[68:71]
	v_mfma_f32_16x16x32_bf16 v[64:67], v[176:179], v[212:215], v[64:67]
	v_mfma_f32_16x16x32_bf16 v[116:119], v[172:175], v[192:195], v[116:119]
	v_mfma_f32_16x16x32_bf16 v[112:115], v[184:187], v[192:195], v[112:115]
	v_mfma_f32_16x16x32_bf16 v[100:103], v[172:175], v[200:203], v[100:103]
	v_mfma_f32_16x16x32_bf16 v[96:99], v[184:187], v[200:203], v[96:99]
	v_mfma_f32_16x16x32_bf16 v[84:87], v[172:175], v[208:211], v[84:87]
	v_mfma_f32_16x16x32_bf16 v[80:83], v[184:187], v[208:211], v[80:83]
	v_mfma_f32_16x16x32_bf16 v[68:71], v[172:175], v[216:219], v[68:71]
	v_mfma_f32_16x16x32_bf16 v[64:67], v[184:187], v[216:219], v[64:67]
	s_barrier
	s_add_i32 s28, s52, s33
	v_lshl_add_u64 v[220:221], v[220:221], 0, s[10:11]
	s_mov_b32 m0, s28
	ds_read_b128 v[188:191], v153 offset:49152
	ds_read_b128 v[192:195], v153 offset:50176
	ds_read_b128 v[196:199], v153 offset:51200
	ds_read_b128 v[200:203], v153 offset:52224
	ds_read_b128 v[204:207], v153 offset:53248
	ds_read_b128 v[208:211], v153 offset:54272
	ds_read_b128 v[212:215], v153 offset:55296
	ds_read_b128 v[216:219], v153 offset:56320
	global_load_lds_dwordx4 v[220:221], off
	s_add_i32 m0, s28, 0x2000
	s_add_u32 s26, s26, 0x40080
	v_lshl_add_u64 v[220:221], v[222:223], 0, s[10:11]
	s_addc_u32 s27, s27, 0
	s_add_i32 s28, s53, s33
	global_load_lds_dwordx4 v[220:221], off
	v_lshl_add_u64 v[220:221], s[26:27], 0, v[130:131]
	s_mov_b32 m0, s28
	s_nop 0
	global_load_lds_dwordx4 v[220:221], off
	v_lshl_add_u64 v[220:221], s[26:27], 0, v[134:135]
	s_add_i32 m0, s28, 0x2000
	s_nop 0
	global_load_lds_dwordx4 v[220:221], off
	v_lshl_add_u64 v[220:221], v[224:225], 0, s[10:11]
	s_mov_b32 m0, s39
	s_nop 0
	global_load_lds_dwordx4 v[220:221], off
	v_lshl_add_u64 v[220:221], v[226:227], 0, s[10:11]
	s_mov_b32 m0, s40
	s_nop 0
	global_load_lds_dwordx4 v[220:221], off
	s_waitcnt vmcnt(6)
	s_waitcnt lgkmcnt(0)
	s_barrier
	s_waitcnt lgkmcnt(0)
	v_mfma_f32_16x16x32_bf16 v[60:63], v[144:147], v[188:191], v[60:63]
	v_mfma_f32_16x16x32_bf16 v[56:59], v[160:163], v[188:191], v[56:59]
	v_mfma_f32_16x16x32_bf16 v[44:47], v[144:147], v[196:199], v[44:47]
	v_mfma_f32_16x16x32_bf16 v[40:43], v[160:163], v[196:199], v[40:43]
	v_mfma_f32_16x16x32_bf16 v[28:31], v[144:147], v[204:207], v[28:31]
	v_mfma_f32_16x16x32_bf16 v[24:27], v[160:163], v[204:207], v[24:27]
	v_mfma_f32_16x16x32_bf16 v[12:15], v[144:147], v[212:215], v[12:15]
	v_mfma_f32_16x16x32_bf16 v[8:11], v[160:163], v[212:215], v[8:11]
	v_mfma_f32_16x16x32_bf16 v[60:63], v[156:159], v[192:195], v[60:63]
	v_mfma_f32_16x16x32_bf16 v[56:59], v[164:167], v[192:195], v[56:59]
	v_mfma_f32_16x16x32_bf16 v[44:47], v[156:159], v[200:203], v[44:47]
	v_mfma_f32_16x16x32_bf16 v[40:43], v[164:167], v[200:203], v[40:43]
	v_mfma_f32_16x16x32_bf16 v[28:31], v[156:159], v[208:211], v[28:31]
	v_mfma_f32_16x16x32_bf16 v[24:27], v[164:167], v[208:211], v[24:27]
	v_mfma_f32_16x16x32_bf16 v[12:15], v[156:159], v[216:219], v[12:15]
	v_mfma_f32_16x16x32_bf16 v[8:11], v[164:167], v[216:219], v[8:11]
	v_mfma_f32_16x16x32_bf16 v[52:55], v[168:171], v[188:191], v[52:55]
	v_mfma_f32_16x16x32_bf16 v[48:51], v[176:179], v[188:191], v[48:51]
	v_mfma_f32_16x16x32_bf16 v[36:39], v[168:171], v[196:199], v[36:39]
	v_mfma_f32_16x16x32_bf16 v[32:35], v[176:179], v[196:199], v[32:35]
	v_mfma_f32_16x16x32_bf16 v[20:23], v[168:171], v[204:207], v[20:23]
	v_mfma_f32_16x16x32_bf16 v[16:19], v[176:179], v[204:207], v[16:19]
	v_mfma_f32_16x16x32_bf16 v[4:7], v[168:171], v[212:215], v[4:7]
	v_mfma_f32_16x16x32_bf16 v[0:3], v[176:179], v[212:215], v[0:3]
	v_mfma_f32_16x16x32_bf16 v[52:55], v[172:175], v[192:195], v[52:55]
	v_mfma_f32_16x16x32_bf16 v[48:51], v[184:187], v[192:195], v[48:51]
	v_mfma_f32_16x16x32_bf16 v[36:39], v[172:175], v[200:203], v[36:39]
	v_mfma_f32_16x16x32_bf16 v[32:35], v[184:187], v[200:203], v[32:35]
	v_mfma_f32_16x16x32_bf16 v[20:23], v[172:175], v[208:211], v[20:23]
	v_mfma_f32_16x16x32_bf16 v[16:19], v[184:187], v[208:211], v[16:19]
	v_mfma_f32_16x16x32_bf16 v[4:7], v[172:175], v[216:219], v[4:7]
	v_mfma_f32_16x16x32_bf16 v[0:3], v[184:187], v[216:219], v[0:3]
	s_barrier
	s_add_i32 s51, s51, 2
	s_add_u32 s24, s24, 0x100
	s_addc_u32 s25, s25, 0
	s_add_u32 s47, s47, 0x100
	s_addc_u32 s50, s50, 0
	s_cmp_gt_u32 s51, 13
	s_cbranch_scc0 .LBB0_617
	s_and_b64 vcc, exec, s[12:13]
	s_cbranch_vccz .LBB0_620
	s_barrier

.LBB0_705:
	ds_read_b128 v[154:157], v151
	ds_read_b128 v[158:161], v151 offset:1024
	ds_read_b128 v[162:165], v151 offset:2048
	ds_read_b128 v[166:169], v151 offset:3072
	ds_read_b128 v[170:173], v152
	ds_read_b128 v[174:177], v152 offset:1024
	ds_read_b128 v[184:187], v152 offset:2048
	ds_read_b128 v[188:191], v152 offset:3072
	s_add_u32 s22, s20, 0xfffc0080
	s_addc_u32 s23, s21, -1
	s_cmp_eq_u32 s50, 12
	s_cselect_b32 s25, s13, s23
	s_cselect_b32 s24, s42, s22
	s_cselect_b32 s23, s11, s47
	s_cselect_b32 s22, s43, s46
	v_lshl_add_u64 v[178:179], s[20:21], 0, v[136:137]
	s_add_i32 m0, s19, 0xc000
	ds_read_b128 v[192:195], v153
	ds_read_b128 v[196:199], v153 offset:1024
	ds_read_b128 v[200:203], v153 offset:2048
	ds_read_b128 v[204:207], v153 offset:3072
	ds_read_b128 v[208:211], v153 offset:4096
	ds_read_b128 v[212:215], v153 offset:5120
	ds_read_b128 v[216:219], v153 offset:6144
	ds_read_b128 v[220:223], v153 offset:7168
	global_load_lds_dwordx4 v[178:179], off
	v_lshl_add_u64 v[178:179], s[20:21], 0, v[138:139]
	s_add_i32 m0, s19, 0xe000
	s_nop 0
	global_load_lds_dwordx4 v[178:179], off
	s_waitcnt vmcnt(8)
	s_waitcnt lgkmcnt(0)
	s_barrier
	s_waitcnt lgkmcnt(0)
	v_mfma_f32_16x16x32_bf16 v[124:127], v[154:157], v[192:195], v[124:127]
	v_mfma_f32_16x16x32_bf16 v[116:119], v[162:165], v[192:195], v[116:119]
	v_mfma_f32_16x16x32_bf16 v[108:111], v[154:157], v[200:203], v[108:111]
	v_mfma_f32_16x16x32_bf16 v[100:103], v[162:165], v[200:203], v[100:103]
	v_mfma_f32_16x16x32_bf16 v[92:95], v[154:157], v[208:211], v[92:95]
	v_mfma_f32_16x16x32_bf16 v[84:87], v[162:165], v[208:211], v[84:87]
	v_mfma_f32_16x16x32_bf16 v[76:79], v[154:157], v[216:219], v[76:79]
	v_mfma_f32_16x16x32_bf16 v[68:71], v[162:165], v[216:219], v[68:71]
	v_mfma_f32_16x16x32_bf16 v[124:127], v[158:161], v[196:199], v[124:127]
	v_mfma_f32_16x16x32_bf16 v[116:119], v[166:169], v[196:199], v[116:119]
	v_mfma_f32_16x16x32_bf16 v[108:111], v[158:161], v[204:207], v[108:111]
	v_mfma_f32_16x16x32_bf16 v[100:103], v[166:169], v[204:207], v[100:103]
	v_mfma_f32_16x16x32_bf16 v[92:95], v[158:161], v[212:215], v[92:95]
	v_mfma_f32_16x16x32_bf16 v[84:87], v[166:169], v[212:215], v[84:87]
	v_mfma_f32_16x16x32_bf16 v[76:79], v[158:161], v[220:223], v[76:79]
	v_mfma_f32_16x16x32_bf16 v[68:71], v[166:169], v[220:223], v[68:71]
	v_mfma_f32_16x16x32_bf16 v[120:123], v[170:173], v[192:195], v[120:123]
	v_mfma_f32_16x16x32_bf16 v[112:115], v[184:187], v[192:195], v[112:115]
	v_mfma_f32_16x16x32_bf16 v[104:107], v[170:173], v[200:203], v[104:107]
	v_mfma_f32_16x16x32_bf16 v[96:99], v[184:187], v[200:203], v[96:99]
	v_mfma_f32_16x16x32_bf16 v[88:91], v[170:173], v[208:211], v[88:91]
	v_mfma_f32_16x16x32_bf16 v[80:83], v[184:187], v[208:211], v[80:83]
	v_mfma_f32_16x16x32_bf16 v[72:75], v[170:173], v[216:219], v[72:75]
	v_mfma_f32_16x16x32_bf16 v[64:67], v[184:187], v[216:219], v[64:67]
	v_mfma_f32_16x16x32_bf16 v[120:123], v[174:177], v[196:199], v[120:123]
	v_mfma_f32_16x16x32_bf16 v[112:115], v[188:191], v[196:199], v[112:115]
	v_mfma_f32_16x16x32_bf16 v[104:107], v[174:177], v[204:207], v[104:107]
	v_mfma_f32_16x16x32_bf16 v[96:99], v[188:191], v[204:207], v[96:99]
	v_mfma_f32_16x16x32_bf16 v[88:91], v[174:177], v[212:215], v[88:91]
	v_mfma_f32_16x16x32_bf16 v[80:83], v[188:191], v[212:215], v[80:83]
	v_mfma_f32_16x16x32_bf16 v[72:75], v[174:177], v[220:223], v[72:75]
	v_mfma_f32_16x16x32_bf16 v[64:67], v[188:191], v[220:223], v[64:67]
	s_barrier
	s_add_i32 s51, s36, s28
	v_lshl_add_u64 v[178:179], s[22:23], 0, v[132:133]
	s_mov_b32 m0, s51
	ds_read_b128 v[192:195], v153 offset:16384
	ds_read_b128 v[196:199], v153 offset:17408
	ds_read_b128 v[200:203], v153 offset:18432
	ds_read_b128 v[204:207], v153 offset:19456
	ds_read_b128 v[208:211], v153 offset:20480
	ds_read_b128 v[212:215], v153 offset:21504
	ds_read_b128 v[216:219], v153 offset:22528
	ds_read_b128 v[220:223], v153 offset:23552
	global_load_lds_dwordx4 v[178:179], off
	s_add_i32 m0, s51, 0x2000
	s_add_u32 s52, s22, 0x40000
	v_lshl_add_u64 v[224:225], s[22:23], 0, v[128:129]
	s_addc_u32 s53, s23, 0
	s_add_i32 s51, s37, s28
	global_load_lds_dwordx4 v[224:225], off
	v_lshl_add_u64 v[226:227], s[52:53], 0, v[132:133]
	s_mov_b32 m0, s51
	global_load_lds_dwordx4 v[226:227], off
	v_lshl_add_u64 v[226:227], s[52:53], 0, v[128:129]
	s_add_i32 m0, s51, 0x2000
	s_nop 0
	global_load_lds_dwordx4 v[226:227], off
	s_waitcnt vmcnt(6)
	s_waitcnt lgkmcnt(0)
	s_barrier
	s_waitcnt lgkmcnt(0)
	v_mfma_f32_16x16x32_bf16 v[60:63], v[154:157], v[192:195], v[60:63]
	v_mfma_f32_16x16x32_bf16 v[52:55], v[162:165], v[192:195], v[52:55]
	v_mfma_f32_16x16x32_bf16 v[44:47], v[154:157], v[200:203], v[44:47]
	v_mfma_f32_16x16x32_bf16 v[36:39], v[162:165], v[200:203], v[36:39]
	v_mfma_f32_16x16x32_bf16 v[28:31], v[154:157], v[208:211], v[28:31]
	v_mfma_f32_16x16x32_bf16 v[20:23], v[162:165], v[208:211], v[20:23]
	v_mfma_f32_16x16x32_bf16 v[12:15], v[154:157], v[216:219], v[12:15]
	v_mfma_f32_16x16x32_bf16 v[4:7], v[162:165], v[216:219], v[4:7]
	v_mfma_f32_16x16x32_bf16 v[60:63], v[158:161], v[196:199], v[60:63]
	v_mfma_f32_16x16x32_bf16 v[52:55], v[166:169], v[196:199], v[52:55]
	v_mfma_f32_16x16x32_bf16 v[44:47], v[158:161], v[204:207], v[44:47]
	v_mfma_f32_16x16x32_bf16 v[36:39], v[166:169], v[204:207], v[36:39]
	v_mfma_f32_16x16x32_bf16 v[28:31], v[158:161], v[212:215], v[28:31]
	v_mfma_f32_16x16x32_bf16 v[20:23], v[166:169], v[212:215], v[20:23]
	v_mfma_f32_16x16x32_bf16 v[12:15], v[158:161], v[220:223], v[12:15]
	v_mfma_f32_16x16x32_bf16 v[4:7], v[166:169], v[220:223], v[4:7]
	v_mfma_f32_16x16x32_bf16 v[56:59], v[170:173], v[192:195], v[56:59]
	v_mfma_f32_16x16x32_bf16 v[48:51], v[184:187], v[192:195], v[48:51]
	v_mfma_f32_16x16x32_bf16 v[40:43], v[170:173], v[200:203], v[40:43]
	v_mfma_f32_16x16x32_bf16 v[32:35], v[184:187], v[200:203], v[32:35]
	v_mfma_f32_16x16x32_bf16 v[24:27], v[170:173], v[208:211], v[24:27]
	v_mfma_f32_16x16x32_bf16 v[16:19], v[184:187], v[208:211], v[16:19]
	v_mfma_f32_16x16x32_bf16 v[8:11], v[170:173], v[216:219], v[8:11]
	v_mfma_f32_16x16x32_bf16 v[0:3], v[184:187], v[216:219], v[0:3]
	v_mfma_f32_16x16x32_bf16 v[56:59], v[174:177], v[196:199], v[56:59]
	v_mfma_f32_16x16x32_bf16 v[48:51], v[188:191], v[196:199], v[48:51]
	v_mfma_f32_16x16x32_bf16 v[40:43], v[174:177], v[204:207], v[40:43]
	v_mfma_f32_16x16x32_bf16 v[32:35], v[188:191], v[204:207], v[32:35]
	v_mfma_f32_16x16x32_bf16 v[24:27], v[174:177], v[212:215], v[24:27]
	v_mfma_f32_16x16x32_bf16 v[16:19], v[188:191], v[212:215], v[16:19]
	v_mfma_f32_16x16x32_bf16 v[8:11], v[174:177], v[220:223], v[8:11]
	v_mfma_f32_16x16x32_bf16 v[0:3], v[188:191], v[220:223], v[0:3]
	s_barrier
	s_add_i32 s51, 0, 0x18000
	s_add_i32 s52, 0, 0x1c000
	v_add_u32_e32 v166, s51, v145
	v_add_u32_e32 v180, s52, v145
	ds_read_b128 v[154:157], v166
	ds_read_b128 v[158:161], v166 offset:1024
	ds_read_b128 v[162:165], v166 offset:2048
	ds_read_b128 v[166:169], v166 offset:3072
	ds_read_b128 v[170:173], v180
	ds_read_b128 v[174:177], v180 offset:1024
	ds_read_b128 v[184:187], v180 offset:2048
	ds_read_b128 v[188:191], v180 offset:3072
	v_lshl_add_u64 v[226:227], s[24:25], 0, v[134:135]
	s_mov_b32 m0, s19
	v_lshl_add_u64 v[228:229], s[24:25], 0, v[130:131]
	global_load_lds_dwordx4 v[226:227], off
	s_mov_b32 m0, s30
	s_nop 0
	global_load_lds_dwordx4 v[228:229], off
	s_add_u32 s24, s24, 0x40000
	s_addc_u32 s25, s25, 0
	s_mov_b32 m0, s31
	v_lshl_add_u64 v[230:231], s[24:25], 0, v[134:135]
	ds_read_b128 v[192:195], v153 offset:32768
	ds_read_b128 v[196:199], v153 offset:33792
	ds_read_b128 v[200:203], v153 offset:34816
	ds_read_b128 v[204:207], v153 offset:35840
	ds_read_b128 v[208:211], v153 offset:36864
	ds_read_b128 v[212:215], v153 offset:37888
	ds_read_b128 v[216:219], v153 offset:38912
	ds_read_b128 v[220:223], v153 offset:39936
	global_load_lds_dwordx4 v[230:231], off
	v_lshl_add_u64 v[230:231], s[24:25], 0, v[130:131]
	s_mov_b32 m0, s33
	s_nop 0
	global_load_lds_dwordx4 v[230:231], off
	s_waitcnt vmcnt(8)
	s_waitcnt lgkmcnt(0)
	s_barrier
	s_waitcnt lgkmcnt(0)
	v_mfma_f32_16x16x32_bf16 v[124:127], v[154:157], v[192:195], v[124:127]
	v_mfma_f32_16x16x32_bf16 v[116:119], v[162:165], v[192:195], v[116:119]
	v_mfma_f32_16x16x32_bf16 v[108:111], v[154:157], v[200:203], v[108:111]
	v_mfma_f32_16x16x32_bf16 v[100:103], v[162:165], v[200:203], v[100:103]
	v_mfma_f32_16x16x32_bf16 v[92:95], v[154:157], v[208:211], v[92:95]
	v_mfma_f32_16x16x32_bf16 v[84:87], v[162:165], v[208:211], v[84:87]
	v_mfma_f32_16x16x32_bf16 v[76:79], v[154:157], v[216:219], v[76:79]
	v_mfma_f32_16x16x32_bf16 v[68:71], v[162:165], v[216:219], v[68:71]
	v_mfma_f32_16x16x32_bf16 v[124:127], v[158:161], v[196:199], v[124:127]
	v_mfma_f32_16x16x32_bf16 v[116:119], v[166:169], v[196:199], v[116:119]
	v_mfma_f32_16x16x32_bf16 v[108:111], v[158:161], v[204:207], v[108:111]
	v_mfma_f32_16x16x32_bf16 v[100:103], v[166:169], v[204:207], v[100:103]
	v_mfma_f32_16x16x32_bf16 v[92:95], v[158:161], v[212:215], v[92:95]
	v_mfma_f32_16x16x32_bf16 v[84:87], v[166:169], v[212:215], v[84:87]
	v_mfma_f32_16x16x32_bf16 v[76:79], v[158:161], v[220:223], v[76:79]
	v_mfma_f32_16x16x32_bf16 v[68:71], v[166:169], v[220:223], v[68:71]
	v_mfma_f32_16x16x32_bf16 v[120:123], v[170:173], v[192:195], v[120:123]
	v_mfma_f32_16x16x32_bf16 v[112:115], v[184:187], v[192:195], v[112:115]
	v_mfma_f32_16x16x32_bf16 v[104:107], v[170:173], v[200:203], v[104:107]
	v_mfma_f32_16x16x32_bf16 v[96:99], v[184:187], v[200:203], v[96:99]
	v_mfma_f32_16x16x32_bf16 v[88:91], v[170:173], v[208:211], v[88:91]
	v_mfma_f32_16x16x32_bf16 v[80:83], v[184:187], v[208:211], v[80:83]
	v_mfma_f32_16x16x32_bf16 v[72:75], v[170:173], v[216:219], v[72:75]
	v_mfma_f32_16x16x32_bf16 v[64:67], v[184:187], v[216:219], v[64:67]
	v_mfma_f32_16x16x32_bf16 v[120:123], v[174:177], v[196:199], v[120:123]
	v_mfma_f32_16x16x32_bf16 v[112:115], v[188:191], v[196:199], v[112:115]
	v_mfma_f32_16x16x32_bf16 v[104:107], v[174:177], v[204:207], v[104:107]
	v_mfma_f32_16x16x32_bf16 v[96:99], v[188:191], v[204:207], v[96:99]
	v_mfma_f32_16x16x32_bf16 v[88:91], v[174:177], v[212:215], v[88:91]
	v_mfma_f32_16x16x32_bf16 v[80:83], v[188:191], v[212:215], v[80:83]
	v_mfma_f32_16x16x32_bf16 v[72:75], v[174:177], v[220:223], v[72:75]
	v_mfma_f32_16x16x32_bf16 v[64:67], v[188:191], v[220:223], v[64:67]
	s_barrier
	s_add_i32 s24, s51, s28
	v_lshl_add_u64 v[178:179], v[178:179], 0, s[6:7]
	s_mov_b32 m0, s24
	ds_read_b128 v[192:195], v153 offset:49152
	ds_read_b128 v[196:199], v153 offset:50176
	ds_read_b128 v[200:203], v153 offset:51200
	ds_read_b128 v[204:207], v153 offset:52224
	ds_read_b128 v[208:211], v153 offset:53248
	ds_read_b128 v[212:215], v153 offset:54272
	ds_read_b128 v[216:219], v153 offset:55296
	ds_read_b128 v[220:223], v153 offset:56320
	global_load_lds_dwordx4 v[178:179], off
	s_add_i32 m0, s24, 0x2000
	s_add_u32 s22, s22, 0x40080
	v_lshl_add_u64 v[178:179], v[224:225], 0, s[6:7]
	s_addc_u32 s23, s23, 0
	s_add_i32 s24, s52, s28
	global_load_lds_dwordx4 v[178:179], off
	v_lshl_add_u64 v[178:179], s[22:23], 0, v[132:133]
	s_mov_b32 m0, s24
	s_nop 0
	global_load_lds_dwordx4 v[178:179], off
	v_lshl_add_u64 v[178:179], s[22:23], 0, v[128:129]
	s_add_i32 m0, s24, 0x2000
	s_nop 0
	global_load_lds_dwordx4 v[178:179], off
	v_lshl_add_u64 v[178:179], v[226:227], 0, s[6:7]
	s_mov_b32 m0, s34
	s_nop 0
	global_load_lds_dwordx4 v[178:179], off
	v_lshl_add_u64 v[178:179], v[228:229], 0, s[6:7]
	s_mov_b32 m0, s35
	s_nop 0
	global_load_lds_dwordx4 v[178:179], off
	s_waitcnt vmcnt(6)
	s_waitcnt lgkmcnt(0)
	s_barrier
	s_waitcnt lgkmcnt(0)
	v_mfma_f32_16x16x32_bf16 v[60:63], v[154:157], v[192:195], v[60:63]
	v_mfma_f32_16x16x32_bf16 v[52:55], v[162:165], v[192:195], v[52:55]
	v_mfma_f32_16x16x32_bf16 v[44:47], v[154:157], v[200:203], v[44:47]
	v_mfma_f32_16x16x32_bf16 v[36:39], v[162:165], v[200:203], v[36:39]
	v_mfma_f32_16x16x32_bf16 v[28:31], v[154:157], v[208:211], v[28:31]
	v_mfma_f32_16x16x32_bf16 v[20:23], v[162:165], v[208:211], v[20:23]
	v_mfma_f32_16x16x32_bf16 v[12:15], v[154:157], v[216:219], v[12:15]
	v_mfma_f32_16x16x32_bf16 v[4:7], v[162:165], v[216:219], v[4:7]
	v_mfma_f32_16x16x32_bf16 v[60:63], v[158:161], v[196:199], v[60:63]
	v_mfma_f32_16x16x32_bf16 v[52:55], v[166:169], v[196:199], v[52:55]
	v_mfma_f32_16x16x32_bf16 v[44:47], v[158:161], v[204:207], v[44:47]
	v_mfma_f32_16x16x32_bf16 v[36:39], v[166:169], v[204:207], v[36:39]
	v_mfma_f32_16x16x32_bf16 v[28:31], v[158:161], v[212:215], v[28:31]
	v_mfma_f32_16x16x32_bf16 v[20:23], v[166:169], v[212:215], v[20:23]
	v_mfma_f32_16x16x32_bf16 v[12:15], v[158:161], v[220:223], v[12:15]
	v_mfma_f32_16x16x32_bf16 v[4:7], v[166:169], v[220:223], v[4:7]
	v_mfma_f32_16x16x32_bf16 v[56:59], v[170:173], v[192:195], v[56:59]
	v_mfma_f32_16x16x32_bf16 v[48:51], v[184:187], v[192:195], v[48:51]
	v_mfma_f32_16x16x32_bf16 v[40:43], v[170:173], v[200:203], v[40:43]
	v_mfma_f32_16x16x32_bf16 v[32:35], v[184:187], v[200:203], v[32:35]
	v_mfma_f32_16x16x32_bf16 v[24:27], v[170:173], v[208:211], v[24:27]
	v_mfma_f32_16x16x32_bf16 v[16:19], v[184:187], v[208:211], v[16:19]
	v_mfma_f32_16x16x32_bf16 v[8:11], v[170:173], v[216:219], v[8:11]
	v_mfma_f32_16x16x32_bf16 v[0:3], v[184:187], v[216:219], v[0:3]
	v_mfma_f32_16x16x32_bf16 v[56:59], v[174:177], v[196:199], v[56:59]
	v_mfma_f32_16x16x32_bf16 v[48:51], v[188:191], v[196:199], v[48:51]
	v_mfma_f32_16x16x32_bf16 v[40:43], v[174:177], v[204:207], v[40:43]
	v_mfma_f32_16x16x32_bf16 v[32:35], v[188:191], v[204:207], v[32:35]
	v_mfma_f32_16x16x32_bf16 v[24:27], v[174:177], v[212:215], v[24:27]
	v_mfma_f32_16x16x32_bf16 v[16:19], v[188:191], v[212:215], v[16:19]
	v_mfma_f32_16x16x32_bf16 v[8:11], v[174:177], v[220:223], v[8:11]
	v_mfma_f32_16x16x32_bf16 v[0:3], v[188:191], v[220:223], v[0:3]
	s_barrier
	s_add_i32 s50, s50, 2
	s_add_u32 s20, s20, 0x100
	s_addc_u32 s21, s21, 0
	s_add_u32 s46, s46, 0x100
	s_addc_u32 s47, s47, 0
	s_cmp_gt_u32 s50, 13
	s_cbranch_scc0 .LBB0_705
	s_and_b64 vcc, exec, s[8:9]
	s_cbranch_vccz .LBB0_708
	s_barrier

.LBB0_787:
	ds_read_b128 v[144:147], v151
	ds_read_b128 v[156:159], v151 offset:1024
	ds_read_b128 v[160:163], v151 offset:2048
	ds_read_b128 v[164:167], v151 offset:3072
	ds_read_b128 v[168:171], v152
	ds_read_b128 v[172:175], v152 offset:1024
	ds_read_b128 v[176:179], v152 offset:2048
	ds_read_b128 v[184:187], v152 offset:3072
	s_add_u32 s20, s18, 0x100
	s_addc_u32 s21, s19, 0
	s_cmp_eq_u32 s47, 40
	s_cselect_b32 s25, s7, s21
	s_cselect_b32 s24, s6, s20
	s_cselect_b32 s23, s17, s46
	s_cselect_b32 s22, s16, s43
	v_lshl_add_u64 v[220:221], s[18:19], 0, v[136:137]
	s_add_i32 m0, s29, 0xc000
	ds_read_b128 v[188:191], v153
	ds_read_b128 v[192:195], v153 offset:1024
	ds_read_b128 v[196:199], v153 offset:2048
	ds_read_b128 v[200:203], v153 offset:3072
	ds_read_b128 v[204:207], v153 offset:4096
	ds_read_b128 v[208:211], v153 offset:5120
	ds_read_b128 v[212:215], v153 offset:6144
	ds_read_b128 v[216:219], v153 offset:7168
	global_load_lds_dwordx4 v[220:221], off
	v_lshl_add_u64 v[220:221], s[18:19], 0, v[138:139]
	s_add_i32 m0, s29, 0xe000
	s_nop 0
	global_load_lds_dwordx4 v[220:221], off
	s_waitcnt vmcnt(8)
	s_waitcnt lgkmcnt(0)
	s_barrier
	s_waitcnt lgkmcnt(0)
	v_mfma_f32_16x16x32_bf16 v[124:127], v[144:147], v[188:191], v[124:127]
	v_mfma_f32_16x16x32_bf16 v[120:123], v[160:163], v[188:191], v[120:123]
	v_mfma_f32_16x16x32_bf16 v[108:111], v[144:147], v[196:199], v[108:111]
	v_mfma_f32_16x16x32_bf16 v[104:107], v[160:163], v[196:199], v[104:107]
	v_mfma_f32_16x16x32_bf16 v[92:95], v[144:147], v[204:207], v[92:95]
	v_mfma_f32_16x16x32_bf16 v[88:91], v[160:163], v[204:207], v[88:91]
	v_mfma_f32_16x16x32_bf16 v[76:79], v[144:147], v[212:215], v[76:79]
	v_mfma_f32_16x16x32_bf16 v[72:75], v[160:163], v[212:215], v[72:75]
	v_mfma_f32_16x16x32_bf16 v[124:127], v[156:159], v[192:195], v[124:127]
	v_mfma_f32_16x16x32_bf16 v[120:123], v[164:167], v[192:195], v[120:123]
	v_mfma_f32_16x16x32_bf16 v[108:111], v[156:159], v[200:203], v[108:111]
	v_mfma_f32_16x16x32_bf16 v[104:107], v[164:167], v[200:203], v[104:107]
	v_mfma_f32_16x16x32_bf16 v[92:95], v[156:159], v[208:211], v[92:95]
	v_mfma_f32_16x16x32_bf16 v[88:91], v[164:167], v[208:211], v[88:91]
	v_mfma_f32_16x16x32_bf16 v[76:79], v[156:159], v[216:219], v[76:79]
	v_mfma_f32_16x16x32_bf16 v[72:75], v[164:167], v[216:219], v[72:75]
	v_mfma_f32_16x16x32_bf16 v[116:119], v[168:171], v[188:191], v[116:119]
	v_mfma_f32_16x16x32_bf16 v[112:115], v[176:179], v[188:191], v[112:115]
	v_mfma_f32_16x16x32_bf16 v[100:103], v[168:171], v[196:199], v[100:103]
	v_mfma_f32_16x16x32_bf16 v[96:99], v[176:179], v[196:199], v[96:99]
	v_mfma_f32_16x16x32_bf16 v[84:87], v[168:171], v[204:207], v[84:87]
	v_mfma_f32_16x16x32_bf16 v[80:83], v[176:179], v[204:207], v[80:83]
	v_mfma_f32_16x16x32_bf16 v[68:71], v[168:171], v[212:215], v[68:71]
	v_mfma_f32_16x16x32_bf16 v[64:67], v[176:179], v[212:215], v[64:67]
	v_mfma_f32_16x16x32_bf16 v[116:119], v[172:175], v[192:195], v[116:119]
	v_mfma_f32_16x16x32_bf16 v[112:115], v[184:187], v[192:195], v[112:115]
	v_mfma_f32_16x16x32_bf16 v[100:103], v[172:175], v[200:203], v[100:103]
	v_mfma_f32_16x16x32_bf16 v[96:99], v[184:187], v[200:203], v[96:99]
	v_mfma_f32_16x16x32_bf16 v[84:87], v[172:175], v[208:211], v[84:87]
	v_mfma_f32_16x16x32_bf16 v[80:83], v[184:187], v[208:211], v[80:83]
	v_mfma_f32_16x16x32_bf16 v[68:71], v[172:175], v[216:219], v[68:71]
	v_mfma_f32_16x16x32_bf16 v[64:67], v[184:187], v[216:219], v[64:67]
	s_barrier
	s_add_i32 s18, s37, s28
	v_lshl_add_u64 v[220:221], s[22:23], 0, v[130:131]
	s_mov_b32 m0, s18
	ds_read_b128 v[188:191], v153 offset:16384
	ds_read_b128 v[192:195], v153 offset:17408
	ds_read_b128 v[196:199], v153 offset:18432
	ds_read_b128 v[200:203], v153 offset:19456
	ds_read_b128 v[204:207], v153 offset:20480
	ds_read_b128 v[208:211], v153 offset:21504
	ds_read_b128 v[212:215], v153 offset:22528
	ds_read_b128 v[216:219], v153 offset:23552
	global_load_lds_dwordx4 v[220:221], off
	s_add_i32 m0, s18, 0x2000
	s_add_u32 s18, s22, 0xb0000
	v_lshl_add_u64 v[222:223], s[22:23], 0, v[134:135]
	s_addc_u32 s19, s23, 0
	s_add_i32 s50, s38, s28
	global_load_lds_dwordx4 v[222:223], off
	v_lshl_add_u64 v[224:225], s[18:19], 0, v[130:131]
	s_mov_b32 m0, s50
	global_load_lds_dwordx4 v[224:225], off
	v_lshl_add_u64 v[224:225], s[18:19], 0, v[134:135]
	s_add_i32 m0, s50, 0x2000
	s_nop 0
	global_load_lds_dwordx4 v[224:225], off
	s_waitcnt vmcnt(6)
	s_waitcnt lgkmcnt(0)
	s_barrier
	s_waitcnt lgkmcnt(0)
	v_mfma_f32_16x16x32_bf16 v[60:63], v[144:147], v[188:191], v[60:63]
	v_mfma_f32_16x16x32_bf16 v[56:59], v[160:163], v[188:191], v[56:59]
	v_mfma_f32_16x16x32_bf16 v[44:47], v[144:147], v[196:199], v[44:47]
	v_mfma_f32_16x16x32_bf16 v[40:43], v[160:163], v[196:199], v[40:43]
	v_mfma_f32_16x16x32_bf16 v[28:31], v[144:147], v[204:207], v[28:31]
	v_mfma_f32_16x16x32_bf16 v[24:27], v[160:163], v[204:207], v[24:27]
	v_mfma_f32_16x16x32_bf16 v[12:15], v[144:147], v[212:215], v[12:15]
	v_mfma_f32_16x16x32_bf16 v[8:11], v[160:163], v[212:215], v[8:11]
	v_mfma_f32_16x16x32_bf16 v[60:63], v[156:159], v[192:195], v[60:63]
	v_mfma_f32_16x16x32_bf16 v[56:59], v[164:167], v[192:195], v[56:59]
	v_mfma_f32_16x16x32_bf16 v[44:47], v[156:159], v[200:203], v[44:47]
	v_mfma_f32_16x16x32_bf16 v[40:43], v[164:167], v[200:203], v[40:43]
	v_mfma_f32_16x16x32_bf16 v[28:31], v[156:159], v[208:211], v[28:31]
	v_mfma_f32_16x16x32_bf16 v[24:27], v[164:167], v[208:211], v[24:27]
	v_mfma_f32_16x16x32_bf16 v[12:15], v[156:159], v[216:219], v[12:15]
	v_mfma_f32_16x16x32_bf16 v[8:11], v[164:167], v[216:219], v[8:11]
	v_mfma_f32_16x16x32_bf16 v[52:55], v[168:171], v[188:191], v[52:55]
	v_mfma_f32_16x16x32_bf16 v[48:51], v[176:179], v[188:191], v[48:51]
	v_mfma_f32_16x16x32_bf16 v[36:39], v[168:171], v[196:199], v[36:39]
	v_mfma_f32_16x16x32_bf16 v[32:35], v[176:179], v[196:199], v[32:35]
	v_mfma_f32_16x16x32_bf16 v[20:23], v[168:171], v[204:207], v[20:23]
	v_mfma_f32_16x16x32_bf16 v[16:19], v[176:179], v[204:207], v[16:19]
	v_mfma_f32_16x16x32_bf16 v[4:7], v[168:171], v[212:215], v[4:7]
	v_mfma_f32_16x16x32_bf16 v[0:3], v[176:179], v[212:215], v[0:3]
	v_mfma_f32_16x16x32_bf16 v[52:55], v[172:175], v[192:195], v[52:55]
	v_mfma_f32_16x16x32_bf16 v[48:51], v[184:187], v[192:195], v[48:51]
	v_mfma_f32_16x16x32_bf16 v[36:39], v[172:175], v[200:203], v[36:39]
	v_mfma_f32_16x16x32_bf16 v[32:35], v[184:187], v[200:203], v[32:35]
	v_mfma_f32_16x16x32_bf16 v[20:23], v[172:175], v[208:211], v[20:23]
	v_mfma_f32_16x16x32_bf16 v[16:19], v[184:187], v[208:211], v[16:19]
	v_mfma_f32_16x16x32_bf16 v[4:7], v[172:175], v[216:219], v[4:7]
	v_mfma_f32_16x16x32_bf16 v[0:3], v[184:187], v[216:219], v[0:3]
	s_barrier
	s_add_i32 s50, 0, 0x18000
	v_add_u32_e32 v155, s50, v149
	s_add_i32 s51, 0, 0x1c000
	ds_read_b128 v[144:147], v155
	ds_read_b128 v[156:159], v155 offset:1024
	ds_read_b128 v[160:163], v155 offset:2048
	ds_read_b128 v[164:167], v155 offset:3072
	v_add_u32_e32 v155, s51, v149
	ds_read_b128 v[168:171], v155
	ds_read_b128 v[172:175], v155 offset:1024
	ds_read_b128 v[176:179], v155 offset:2048
	ds_read_b128 v[184:187], v155 offset:3072
	s_add_u32 s18, s24, 0xb0000
	s_addc_u32 s19, s25, 0
	v_lshl_add_u64 v[224:225], s[24:25], 0, v[128:129]
	s_mov_b32 m0, s29
	v_lshl_add_u64 v[226:227], s[24:25], 0, v[132:133]
	global_load_lds_dwordx4 v[224:225], off
	s_mov_b32 m0, s30
	s_nop 0
	global_load_lds_dwordx4 v[226:227], off
	s_mov_b32 m0, s31
	v_lshl_add_u64 v[228:229], s[18:19], 0, v[128:129]
	ds_read_b128 v[188:191], v153 offset:32768
	ds_read_b128 v[192:195], v153 offset:33792
	ds_read_b128 v[196:199], v153 offset:34816
	ds_read_b128 v[200:203], v153 offset:35840
	ds_read_b128 v[204:207], v153 offset:36864
	ds_read_b128 v[208:211], v153 offset:37888
	ds_read_b128 v[212:215], v153 offset:38912
	ds_read_b128 v[216:219], v153 offset:39936
	global_load_lds_dwordx4 v[228:229], off
	v_lshl_add_u64 v[228:229], s[18:19], 0, v[132:133]
	s_mov_b32 m0, s33
	s_nop 0
	global_load_lds_dwordx4 v[228:229], off
	s_waitcnt vmcnt(8)
	s_waitcnt lgkmcnt(0)
	s_barrier
	s_waitcnt lgkmcnt(0)
	v_mfma_f32_16x16x32_bf16 v[124:127], v[144:147], v[188:191], v[124:127]
	v_mfma_f32_16x16x32_bf16 v[120:123], v[160:163], v[188:191], v[120:123]
	v_mfma_f32_16x16x32_bf16 v[108:111], v[144:147], v[196:199], v[108:111]
	v_mfma_f32_16x16x32_bf16 v[104:107], v[160:163], v[196:199], v[104:107]
	v_mfma_f32_16x16x32_bf16 v[92:95], v[144:147], v[204:207], v[92:95]
	v_mfma_f32_16x16x32_bf16 v[88:91], v[160:163], v[204:207], v[88:91]
	v_mfma_f32_16x16x32_bf16 v[76:79], v[144:147], v[212:215], v[76:79]
	v_mfma_f32_16x16x32_bf16 v[72:75], v[160:163], v[212:215], v[72:75]
	v_mfma_f32_16x16x32_bf16 v[124:127], v[156:159], v[192:195], v[124:127]
	v_mfma_f32_16x16x32_bf16 v[120:123], v[164:167], v[192:195], v[120:123]
	v_mfma_f32_16x16x32_bf16 v[108:111], v[156:159], v[200:203], v[108:111]
	v_mfma_f32_16x16x32_bf16 v[104:107], v[164:167], v[200:203], v[104:107]
	v_mfma_f32_16x16x32_bf16 v[92:95], v[156:159], v[208:211], v[92:95]
	v_mfma_f32_16x16x32_bf16 v[88:91], v[164:167], v[208:211], v[88:91]
	v_mfma_f32_16x16x32_bf16 v[76:79], v[156:159], v[216:219], v[76:79]
	v_mfma_f32_16x16x32_bf16 v[72:75], v[164:167], v[216:219], v[72:75]
	v_mfma_f32_16x16x32_bf16 v[116:119], v[168:171], v[188:191], v[116:119]
	v_mfma_f32_16x16x32_bf16 v[112:115], v[176:179], v[188:191], v[112:115]
	v_mfma_f32_16x16x32_bf16 v[100:103], v[168:171], v[196:199], v[100:103]
	v_mfma_f32_16x16x32_bf16 v[96:99], v[176:179], v[196:199], v[96:99]
	v_mfma_f32_16x16x32_bf16 v[84:87], v[168:171], v[204:207], v[84:87]
	v_mfma_f32_16x16x32_bf16 v[80:83], v[176:179], v[204:207], v[80:83]
	v_mfma_f32_16x16x32_bf16 v[68:71], v[168:171], v[212:215], v[68:71]
	v_mfma_f32_16x16x32_bf16 v[64:67], v[176:179], v[212:215], v[64:67]
	v_mfma_f32_16x16x32_bf16 v[116:119], v[172:175], v[192:195], v[116:119]
	v_mfma_f32_16x16x32_bf16 v[112:115], v[184:187], v[192:195], v[112:115]
	v_mfma_f32_16x16x32_bf16 v[100:103], v[172:175], v[200:203], v[100:103]
	v_mfma_f32_16x16x32_bf16 v[96:99], v[184:187], v[200:203], v[96:99]
	v_mfma_f32_16x16x32_bf16 v[84:87], v[172:175], v[208:211], v[84:87]
	v_mfma_f32_16x16x32_bf16 v[80:83], v[184:187], v[208:211], v[80:83]
	v_mfma_f32_16x16x32_bf16 v[68:71], v[172:175], v[216:219], v[68:71]
	v_mfma_f32_16x16x32_bf16 v[64:67], v[184:187], v[216:219], v[64:67]
	s_barrier
	s_add_i32 s18, s50, s28
	v_lshl_add_u64 v[220:221], v[220:221], 0, s[12:13]
	s_mov_b32 m0, s18
	ds_read_b128 v[188:191], v153 offset:49152
	ds_read_b128 v[192:195], v153 offset:50176
	ds_read_b128 v[196:199], v153 offset:51200
	ds_read_b128 v[200:203], v153 offset:52224
	ds_read_b128 v[204:207], v153 offset:53248
	ds_read_b128 v[208:211], v153 offset:54272
	ds_read_b128 v[212:215], v153 offset:55296
	ds_read_b128 v[216:219], v153 offset:56320
	global_load_lds_dwordx4 v[220:221], off
	s_add_i32 m0, s18, 0x2000
	s_add_u32 s18, s22, 0xb0080
	v_lshl_add_u64 v[220:221], v[222:223], 0, s[12:13]
	s_addc_u32 s19, s23, 0
	s_add_i32 s22, s51, s28
	global_load_lds_dwordx4 v[220:221], off
	v_lshl_add_u64 v[220:221], s[18:19], 0, v[130:131]
	s_mov_b32 m0, s22
	s_nop 0
	global_load_lds_dwordx4 v[220:221], off
	v_lshl_add_u64 v[220:221], s[18:19], 0, v[134:135]
	s_add_i32 m0, s22, 0x2000
	s_nop 0
	global_load_lds_dwordx4 v[220:221], off
	v_lshl_add_u64 v[220:221], v[224:225], 0, s[12:13]
	s_mov_b32 m0, s35
	s_nop 0
	global_load_lds_dwordx4 v[220:221], off
	v_lshl_add_u64 v[220:221], v[226:227], 0, s[12:13]
	s_mov_b32 m0, s36
	s_nop 0
	global_load_lds_dwordx4 v[220:221], off
	s_waitcnt vmcnt(6)
	s_waitcnt lgkmcnt(0)
	s_barrier
	s_waitcnt lgkmcnt(0)
	v_mfma_f32_16x16x32_bf16 v[60:63], v[144:147], v[188:191], v[60:63]
	v_mfma_f32_16x16x32_bf16 v[56:59], v[160:163], v[188:191], v[56:59]
	v_mfma_f32_16x16x32_bf16 v[44:47], v[144:147], v[196:199], v[44:47]
	v_mfma_f32_16x16x32_bf16 v[40:43], v[160:163], v[196:199], v[40:43]
	v_mfma_f32_16x16x32_bf16 v[28:31], v[144:147], v[204:207], v[28:31]
	v_mfma_f32_16x16x32_bf16 v[24:27], v[160:163], v[204:207], v[24:27]
	v_mfma_f32_16x16x32_bf16 v[12:15], v[144:147], v[212:215], v[12:15]
	v_mfma_f32_16x16x32_bf16 v[8:11], v[160:163], v[212:215], v[8:11]
	v_mfma_f32_16x16x32_bf16 v[60:63], v[156:159], v[192:195], v[60:63]
	v_mfma_f32_16x16x32_bf16 v[56:59], v[164:167], v[192:195], v[56:59]
	v_mfma_f32_16x16x32_bf16 v[44:47], v[156:159], v[200:203], v[44:47]
	v_mfma_f32_16x16x32_bf16 v[40:43], v[164:167], v[200:203], v[40:43]
	v_mfma_f32_16x16x32_bf16 v[28:31], v[156:159], v[208:211], v[28:31]
	v_mfma_f32_16x16x32_bf16 v[24:27], v[164:167], v[208:211], v[24:27]
	v_mfma_f32_16x16x32_bf16 v[12:15], v[156:159], v[216:219], v[12:15]
	v_mfma_f32_16x16x32_bf16 v[8:11], v[164:167], v[216:219], v[8:11]
	v_mfma_f32_16x16x32_bf16 v[52:55], v[168:171], v[188:191], v[52:55]
	v_mfma_f32_16x16x32_bf16 v[48:51], v[176:179], v[188:191], v[48:51]
	v_mfma_f32_16x16x32_bf16 v[36:39], v[168:171], v[196:199], v[36:39]
	v_mfma_f32_16x16x32_bf16 v[32:35], v[176:179], v[196:199], v[32:35]
	v_mfma_f32_16x16x32_bf16 v[20:23], v[168:171], v[204:207], v[20:23]
	v_mfma_f32_16x16x32_bf16 v[16:19], v[176:179], v[204:207], v[16:19]
	v_mfma_f32_16x16x32_bf16 v[4:7], v[168:171], v[212:215], v[4:7]
	v_mfma_f32_16x16x32_bf16 v[0:3], v[176:179], v[212:215], v[0:3]
	v_mfma_f32_16x16x32_bf16 v[52:55], v[172:175], v[192:195], v[52:55]
	v_mfma_f32_16x16x32_bf16 v[48:51], v[184:187], v[192:195], v[48:51]
	v_mfma_f32_16x16x32_bf16 v[36:39], v[172:175], v[200:203], v[36:39]
	v_mfma_f32_16x16x32_bf16 v[32:35], v[184:187], v[200:203], v[32:35]
	v_mfma_f32_16x16x32_bf16 v[20:23], v[172:175], v[208:211], v[20:23]
	v_mfma_f32_16x16x32_bf16 v[16:19], v[184:187], v[208:211], v[16:19]
	v_mfma_f32_16x16x32_bf16 v[4:7], v[172:175], v[216:219], v[4:7]
	v_mfma_f32_16x16x32_bf16 v[0:3], v[184:187], v[216:219], v[0:3]
	s_barrier
	s_add_i32 s47, s47, 2
	s_add_u32 s43, s43, 0x100
	s_addc_u32 s46, s46, 0
	s_cmp_gt_u32 s47, 41
	s_mov_b64 s[18:19], s[20:21]
	s_cbranch_scc0 .LBB0_787
	s_and_b64 vcc, exec, s[14:15]
	s_cbranch_vccz .LBB0_790
	s_barrier

.LBB0_877:
	ds_read_b128 v[144:147], v173
	ds_read_b128 v[148:151], v173 offset:1024
	ds_read_b128 v[152:155], v173 offset:2048
	ds_read_b128 v[156:159], v173 offset:3072
	ds_read_b128 v[184:187], v174
	ds_read_b128 v[188:191], v174 offset:1024
	ds_read_b128 v[192:195], v174 offset:2048
	ds_read_b128 v[196:199], v174 offset:3072
	s_add_u32 s30, s28, 0xfffc0080
	s_addc_u32 s31, s29, -1
	s_cmp_eq_u32 s56, 12
	s_cselect_b32 s35, s11, s31
	s_cselect_b32 s34, s23, s30
	s_cselect_b32 s31, s21, s55
	s_cselect_b32 s30, s53, s54
	v_lshl_add_u64 v[160:161], s[28:29], 0, v[136:137]
	s_add_i32 m0, s38, 0xc000
	ds_read_b128 v[200:203], v175
	ds_read_b128 v[204:207], v175 offset:1024
	ds_read_b128 v[208:211], v175 offset:2048
	ds_read_b128 v[212:215], v175 offset:3072
	ds_read_b128 v[216:219], v175 offset:4096
	ds_read_b128 v[220:223], v175 offset:5120
	ds_read_b128 v[224:227], v175 offset:6144
	ds_read_b128 v[228:231], v175 offset:7168
	global_load_lds_dwordx4 v[160:161], off
	v_lshl_add_u64 v[160:161], s[28:29], 0, v[138:139]
	s_add_i32 m0, s38, 0xe000
	s_nop 0
	global_load_lds_dwordx4 v[160:161], off
	s_waitcnt vmcnt(8)
	s_waitcnt lgkmcnt(0)
	s_barrier
	s_waitcnt lgkmcnt(0)
	v_mfma_f32_16x16x32_bf16 v[124:127], v[144:147], v[200:203], v[124:127]
	v_mfma_f32_16x16x32_bf16 v[120:123], v[152:155], v[200:203], v[120:123]
	v_mfma_f32_16x16x32_bf16 v[108:111], v[144:147], v[208:211], v[108:111]
	v_mfma_f32_16x16x32_bf16 v[104:107], v[152:155], v[208:211], v[104:107]
	v_mfma_f32_16x16x32_bf16 v[92:95], v[144:147], v[216:219], v[92:95]
	v_mfma_f32_16x16x32_bf16 v[88:91], v[152:155], v[216:219], v[88:91]
	v_mfma_f32_16x16x32_bf16 v[76:79], v[144:147], v[224:227], v[76:79]
	v_mfma_f32_16x16x32_bf16 v[72:75], v[152:155], v[224:227], v[72:75]
	v_mfma_f32_16x16x32_bf16 v[124:127], v[148:151], v[204:207], v[124:127]
	v_mfma_f32_16x16x32_bf16 v[120:123], v[156:159], v[204:207], v[120:123]
	v_mfma_f32_16x16x32_bf16 v[108:111], v[148:151], v[212:215], v[108:111]
	v_mfma_f32_16x16x32_bf16 v[104:107], v[156:159], v[212:215], v[104:107]
	v_mfma_f32_16x16x32_bf16 v[92:95], v[148:151], v[220:223], v[92:95]
	v_mfma_f32_16x16x32_bf16 v[88:91], v[156:159], v[220:223], v[88:91]
	v_mfma_f32_16x16x32_bf16 v[76:79], v[148:151], v[228:231], v[76:79]
	v_mfma_f32_16x16x32_bf16 v[72:75], v[156:159], v[228:231], v[72:75]
	v_mfma_f32_16x16x32_bf16 v[116:119], v[184:187], v[200:203], v[116:119]
	v_mfma_f32_16x16x32_bf16 v[112:115], v[192:195], v[200:203], v[112:115]
	v_mfma_f32_16x16x32_bf16 v[100:103], v[184:187], v[208:211], v[100:103]
	v_mfma_f32_16x16x32_bf16 v[96:99], v[192:195], v[208:211], v[96:99]
	v_mfma_f32_16x16x32_bf16 v[84:87], v[184:187], v[216:219], v[84:87]
	v_mfma_f32_16x16x32_bf16 v[80:83], v[192:195], v[216:219], v[80:83]
	v_mfma_f32_16x16x32_bf16 v[68:71], v[184:187], v[224:227], v[68:71]
	v_mfma_f32_16x16x32_bf16 v[64:67], v[192:195], v[224:227], v[64:67]
	v_mfma_f32_16x16x32_bf16 v[116:119], v[188:191], v[204:207], v[116:119]
	v_mfma_f32_16x16x32_bf16 v[112:115], v[196:199], v[204:207], v[112:115]
	v_mfma_f32_16x16x32_bf16 v[100:103], v[188:191], v[212:215], v[100:103]
	v_mfma_f32_16x16x32_bf16 v[96:99], v[196:199], v[212:215], v[96:99]
	v_mfma_f32_16x16x32_bf16 v[84:87], v[188:191], v[220:223], v[84:87]
	v_mfma_f32_16x16x32_bf16 v[80:83], v[196:199], v[220:223], v[80:83]
	v_mfma_f32_16x16x32_bf16 v[68:71], v[188:191], v[228:231], v[68:71]
	v_mfma_f32_16x16x32_bf16 v[64:67], v[196:199], v[228:231], v[64:67]
	s_barrier
	s_add_i32 s57, s47, s37
	v_lshl_add_u64 v[160:161], s[30:31], 0, v[130:131]
	s_mov_b32 m0, s57
	ds_read_b128 v[200:203], v175 offset:16384
	ds_read_b128 v[204:207], v175 offset:17408
	ds_read_b128 v[208:211], v175 offset:18432
	ds_read_b128 v[212:215], v175 offset:19456
	ds_read_b128 v[216:219], v175 offset:20480
	ds_read_b128 v[220:223], v175 offset:21504
	ds_read_b128 v[224:227], v175 offset:22528
	ds_read_b128 v[228:231], v175 offset:23552
	global_load_lds_dwordx4 v[160:161], off
	s_add_i32 m0, s57, 0x2000
	s_add_u32 s58, s30, 0x40000
	v_lshl_add_u64 v[178:179], s[30:31], 0, v[134:135]
	s_addc_u32 s59, s31, 0
	s_add_i32 s57, s50, s37
	global_load_lds_dwordx4 v[178:179], off
	v_lshl_add_u64 v[232:233], s[58:59], 0, v[130:131]
	s_mov_b32 m0, s57
	global_load_lds_dwordx4 v[232:233], off
	v_lshl_add_u64 v[232:233], s[58:59], 0, v[134:135]
	s_add_i32 m0, s57, 0x2000
	s_nop 0
	global_load_lds_dwordx4 v[232:233], off
	s_waitcnt vmcnt(6)
	s_waitcnt lgkmcnt(0)
	s_barrier
	s_waitcnt lgkmcnt(0)
	v_mfma_f32_16x16x32_bf16 v[60:63], v[144:147], v[200:203], v[60:63]
	v_mfma_f32_16x16x32_bf16 v[56:59], v[152:155], v[200:203], v[56:59]
	v_mfma_f32_16x16x32_bf16 v[44:47], v[144:147], v[208:211], v[44:47]
	v_mfma_f32_16x16x32_bf16 v[40:43], v[152:155], v[208:211], v[40:43]
	v_mfma_f32_16x16x32_bf16 v[28:31], v[144:147], v[216:219], v[28:31]
	v_mfma_f32_16x16x32_bf16 v[24:27], v[152:155], v[216:219], v[24:27]
	v_mfma_f32_16x16x32_bf16 v[12:15], v[144:147], v[224:227], v[12:15]
	v_mfma_f32_16x16x32_bf16 v[8:11], v[152:155], v[224:227], v[8:11]
	v_mfma_f32_16x16x32_bf16 v[60:63], v[148:151], v[204:207], v[60:63]
	v_mfma_f32_16x16x32_bf16 v[56:59], v[156:159], v[204:207], v[56:59]
	v_mfma_f32_16x16x32_bf16 v[44:47], v[148:151], v[212:215], v[44:47]
	v_mfma_f32_16x16x32_bf16 v[40:43], v[156:159], v[212:215], v[40:43]
	v_mfma_f32_16x16x32_bf16 v[28:31], v[148:151], v[220:223], v[28:31]
	v_mfma_f32_16x16x32_bf16 v[24:27], v[156:159], v[220:223], v[24:27]
	v_mfma_f32_16x16x32_bf16 v[12:15], v[148:151], v[228:231], v[12:15]
	v_mfma_f32_16x16x32_bf16 v[8:11], v[156:159], v[228:231], v[8:11]
	v_mfma_f32_16x16x32_bf16 v[52:55], v[184:187], v[200:203], v[52:55]
	v_mfma_f32_16x16x32_bf16 v[48:51], v[192:195], v[200:203], v[48:51]
	v_mfma_f32_16x16x32_bf16 v[36:39], v[184:187], v[208:211], v[36:39]
	v_mfma_f32_16x16x32_bf16 v[32:35], v[192:195], v[208:211], v[32:35]
	v_mfma_f32_16x16x32_bf16 v[20:23], v[184:187], v[216:219], v[20:23]
	v_mfma_f32_16x16x32_bf16 v[16:19], v[192:195], v[216:219], v[16:19]
	v_mfma_f32_16x16x32_bf16 v[4:7], v[184:187], v[224:227], v[4:7]
	v_mfma_f32_16x16x32_bf16 v[0:3], v[192:195], v[224:227], v[0:3]
	v_mfma_f32_16x16x32_bf16 v[52:55], v[188:191], v[204:207], v[52:55]
	v_mfma_f32_16x16x32_bf16 v[48:51], v[196:199], v[204:207], v[48:51]
	v_mfma_f32_16x16x32_bf16 v[36:39], v[188:191], v[212:215], v[36:39]
	v_mfma_f32_16x16x32_bf16 v[32:35], v[196:199], v[212:215], v[32:35]
	v_mfma_f32_16x16x32_bf16 v[20:23], v[188:191], v[220:223], v[20:23]
	v_mfma_f32_16x16x32_bf16 v[16:19], v[196:199], v[220:223], v[16:19]
	v_mfma_f32_16x16x32_bf16 v[4:7], v[188:191], v[228:231], v[4:7]
	v_mfma_f32_16x16x32_bf16 v[0:3], v[196:199], v[228:231], v[0:3]
	s_barrier
	s_add_i32 s57, 0, 0x18000
	s_add_i32 s58, 0, 0x1c000
	v_add_u32_e32 v156, s57, v163
	v_add_u32_e32 v177, s58, v163
	ds_read_b128 v[144:147], v156
	ds_read_b128 v[148:151], v156 offset:1024
	ds_read_b128 v[152:155], v156 offset:2048
	ds_read_b128 v[156:159], v156 offset:3072
	ds_read_b128 v[184:187], v177
	ds_read_b128 v[188:191], v177 offset:1024
	ds_read_b128 v[192:195], v177 offset:2048
	ds_read_b128 v[196:199], v177 offset:3072
	v_lshl_add_u64 v[232:233], s[34:35], 0, v[128:129]
	s_mov_b32 m0, s38
	v_lshl_add_u64 v[234:235], s[34:35], 0, v[132:133]
	global_load_lds_dwordx4 v[232:233], off
	s_mov_b32 m0, s39
	s_nop 0
	global_load_lds_dwordx4 v[234:235], off
	s_add_u32 s34, s34, 0x40000
	s_addc_u32 s35, s35, 0
	s_mov_b32 m0, s40
	v_lshl_add_u64 v[236:237], s[34:35], 0, v[128:129]
	ds_read_b128 v[200:203], v175 offset:32768
	ds_read_b128 v[204:207], v175 offset:33792
	ds_read_b128 v[208:211], v175 offset:34816
	ds_read_b128 v[212:215], v175 offset:35840
	ds_read_b128 v[216:219], v175 offset:36864
	ds_read_b128 v[220:223], v175 offset:37888
	ds_read_b128 v[224:227], v175 offset:38912
	ds_read_b128 v[228:231], v175 offset:39936
	global_load_lds_dwordx4 v[236:237], off
	v_lshl_add_u64 v[236:237], s[34:35], 0, v[132:133]
	s_mov_b32 m0, s41
	s_nop 0
	global_load_lds_dwordx4 v[236:237], off
	s_waitcnt vmcnt(8)
	s_waitcnt lgkmcnt(0)
	s_barrier
	s_waitcnt lgkmcnt(0)
	v_mfma_f32_16x16x32_bf16 v[124:127], v[144:147], v[200:203], v[124:127]
	v_mfma_f32_16x16x32_bf16 v[120:123], v[152:155], v[200:203], v[120:123]
	v_mfma_f32_16x16x32_bf16 v[108:111], v[144:147], v[208:211], v[108:111]
	v_mfma_f32_16x16x32_bf16 v[104:107], v[152:155], v[208:211], v[104:107]
	v_mfma_f32_16x16x32_bf16 v[92:95], v[144:147], v[216:219], v[92:95]
	v_mfma_f32_16x16x32_bf16 v[88:91], v[152:155], v[216:219], v[88:91]
	v_mfma_f32_16x16x32_bf16 v[76:79], v[144:147], v[224:227], v[76:79]
	v_mfma_f32_16x16x32_bf16 v[72:75], v[152:155], v[224:227], v[72:75]
	v_mfma_f32_16x16x32_bf16 v[124:127], v[148:151], v[204:207], v[124:127]
	v_mfma_f32_16x16x32_bf16 v[120:123], v[156:159], v[204:207], v[120:123]
	v_mfma_f32_16x16x32_bf16 v[108:111], v[148:151], v[212:215], v[108:111]
	v_mfma_f32_16x16x32_bf16 v[104:107], v[156:159], v[212:215], v[104:107]
	v_mfma_f32_16x16x32_bf16 v[92:95], v[148:151], v[220:223], v[92:95]
	v_mfma_f32_16x16x32_bf16 v[88:91], v[156:159], v[220:223], v[88:91]
	v_mfma_f32_16x16x32_bf16 v[76:79], v[148:151], v[228:231], v[76:79]
	v_mfma_f32_16x16x32_bf16 v[72:75], v[156:159], v[228:231], v[72:75]
	v_mfma_f32_16x16x32_bf16 v[116:119], v[184:187], v[200:203], v[116:119]
	v_mfma_f32_16x16x32_bf16 v[112:115], v[192:195], v[200:203], v[112:115]
	v_mfma_f32_16x16x32_bf16 v[100:103], v[184:187], v[208:211], v[100:103]
	v_mfma_f32_16x16x32_bf16 v[96:99], v[192:195], v[208:211], v[96:99]
	v_mfma_f32_16x16x32_bf16 v[84:87], v[184:187], v[216:219], v[84:87]
	v_mfma_f32_16x16x32_bf16 v[80:83], v[192:195], v[216:219], v[80:83]
	v_mfma_f32_16x16x32_bf16 v[68:71], v[184:187], v[224:227], v[68:71]
	v_mfma_f32_16x16x32_bf16 v[64:67], v[192:195], v[224:227], v[64:67]
	v_mfma_f32_16x16x32_bf16 v[116:119], v[188:191], v[204:207], v[116:119]
	v_mfma_f32_16x16x32_bf16 v[112:115], v[196:199], v[204:207], v[112:115]
	v_mfma_f32_16x16x32_bf16 v[100:103], v[188:191], v[212:215], v[100:103]
	v_mfma_f32_16x16x32_bf16 v[96:99], v[196:199], v[212:215], v[96:99]
	v_mfma_f32_16x16x32_bf16 v[84:87], v[188:191], v[220:223], v[84:87]
	v_mfma_f32_16x16x32_bf16 v[80:83], v[196:199], v[220:223], v[80:83]
	v_mfma_f32_16x16x32_bf16 v[68:71], v[188:191], v[228:231], v[68:71]
	v_mfma_f32_16x16x32_bf16 v[64:67], v[196:199], v[228:231], v[64:67]
	s_barrier
	s_add_i32 s34, s57, s37
	v_lshl_add_u64 v[160:161], v[160:161], 0, s[14:15]
	s_mov_b32 m0, s34
	ds_read_b128 v[200:203], v175 offset:49152
	ds_read_b128 v[204:207], v175 offset:50176
	ds_read_b128 v[208:211], v175 offset:51200
	ds_read_b128 v[212:215], v175 offset:52224
	ds_read_b128 v[216:219], v175 offset:53248
	ds_read_b128 v[220:223], v175 offset:54272
	ds_read_b128 v[224:227], v175 offset:55296
	ds_read_b128 v[228:231], v175 offset:56320
	global_load_lds_dwordx4 v[160:161], off
	s_add_i32 m0, s34, 0x2000
	s_add_u32 s30, s30, 0x40080
	v_lshl_add_u64 v[160:161], v[178:179], 0, s[14:15]
	s_addc_u32 s31, s31, 0
	s_add_i32 s34, s58, s37
	global_load_lds_dwordx4 v[160:161], off
	v_lshl_add_u64 v[160:161], s[30:31], 0, v[130:131]
	s_mov_b32 m0, s34
	s_nop 0
	global_load_lds_dwordx4 v[160:161], off
	v_lshl_add_u64 v[160:161], s[30:31], 0, v[134:135]
	s_add_i32 m0, s34, 0x2000
	s_nop 0
	global_load_lds_dwordx4 v[160:161], off
	v_lshl_add_u64 v[160:161], v[232:233], 0, s[14:15]
	s_mov_b32 m0, s42
	s_nop 0
	global_load_lds_dwordx4 v[160:161], off
	v_lshl_add_u64 v[160:161], v[234:235], 0, s[14:15]
	s_mov_b32 m0, s43
	s_nop 0
	global_load_lds_dwordx4 v[160:161], off
	s_waitcnt vmcnt(6)
	s_waitcnt lgkmcnt(0)
	s_barrier
	s_waitcnt lgkmcnt(0)
	v_mfma_f32_16x16x32_bf16 v[60:63], v[144:147], v[200:203], v[60:63]
	v_mfma_f32_16x16x32_bf16 v[56:59], v[152:155], v[200:203], v[56:59]
	v_mfma_f32_16x16x32_bf16 v[44:47], v[144:147], v[208:211], v[44:47]
	v_mfma_f32_16x16x32_bf16 v[40:43], v[152:155], v[208:211], v[40:43]
	v_mfma_f32_16x16x32_bf16 v[28:31], v[144:147], v[216:219], v[28:31]
	v_mfma_f32_16x16x32_bf16 v[24:27], v[152:155], v[216:219], v[24:27]
	v_mfma_f32_16x16x32_bf16 v[12:15], v[144:147], v[224:227], v[12:15]
	v_mfma_f32_16x16x32_bf16 v[8:11], v[152:155], v[224:227], v[8:11]
	v_mfma_f32_16x16x32_bf16 v[60:63], v[148:151], v[204:207], v[60:63]
	v_mfma_f32_16x16x32_bf16 v[56:59], v[156:159], v[204:207], v[56:59]
	v_mfma_f32_16x16x32_bf16 v[44:47], v[148:151], v[212:215], v[44:47]
	v_mfma_f32_16x16x32_bf16 v[40:43], v[156:159], v[212:215], v[40:43]
	v_mfma_f32_16x16x32_bf16 v[28:31], v[148:151], v[220:223], v[28:31]
	v_mfma_f32_16x16x32_bf16 v[24:27], v[156:159], v[220:223], v[24:27]
	v_mfma_f32_16x16x32_bf16 v[12:15], v[148:151], v[228:231], v[12:15]
	v_mfma_f32_16x16x32_bf16 v[8:11], v[156:159], v[228:231], v[8:11]
	v_mfma_f32_16x16x32_bf16 v[52:55], v[184:187], v[200:203], v[52:55]
	v_mfma_f32_16x16x32_bf16 v[48:51], v[192:195], v[200:203], v[48:51]
	v_mfma_f32_16x16x32_bf16 v[36:39], v[184:187], v[208:211], v[36:39]
	v_mfma_f32_16x16x32_bf16 v[32:35], v[192:195], v[208:211], v[32:35]
	v_mfma_f32_16x16x32_bf16 v[20:23], v[184:187], v[216:219], v[20:23]
	v_mfma_f32_16x16x32_bf16 v[16:19], v[192:195], v[216:219], v[16:19]
	v_mfma_f32_16x16x32_bf16 v[4:7], v[184:187], v[224:227], v[4:7]
	v_mfma_f32_16x16x32_bf16 v[0:3], v[192:195], v[224:227], v[0:3]
	v_mfma_f32_16x16x32_bf16 v[52:55], v[188:191], v[204:207], v[52:55]
	v_mfma_f32_16x16x32_bf16 v[48:51], v[196:199], v[204:207], v[48:51]
	v_mfma_f32_16x16x32_bf16 v[36:39], v[188:191], v[212:215], v[36:39]
	v_mfma_f32_16x16x32_bf16 v[32:35], v[196:199], v[212:215], v[32:35]
	v_mfma_f32_16x16x32_bf16 v[20:23], v[188:191], v[220:223], v[20:23]
	v_mfma_f32_16x16x32_bf16 v[16:19], v[196:199], v[220:223], v[16:19]
	v_mfma_f32_16x16x32_bf16 v[4:7], v[188:191], v[228:231], v[4:7]
	v_mfma_f32_16x16x32_bf16 v[0:3], v[196:199], v[228:231], v[0:3]
	s_barrier
	s_add_i32 s56, s56, 2
	s_add_u32 s28, s28, 0x100
	s_addc_u32 s29, s29, 0
	s_add_u32 s54, s54, 0x100
	s_addc_u32 s55, s55, 0
	s_cmp_gt_u32 s56, 13
	s_cbranch_scc0 .LBB0_877
	s_and_b64 vcc, exec, s[16:17]
	s_cbranch_vccz .LBB0_880
	s_barrier

.LBB0_1291:
	ds_read_b128 v[144:147], v151
	ds_read_b128 v[156:159], v151 offset:1024
	ds_read_b128 v[160:163], v151 offset:2048
	ds_read_b128 v[164:167], v151 offset:3072
	ds_read_b128 v[168:171], v152
	ds_read_b128 v[172:175], v152 offset:1024
	ds_read_b128 v[176:179], v152 offset:2048
	ds_read_b128 v[184:187], v152 offset:3072
	s_add_u32 s26, s24, 0xfffc0080
	s_addc_u32 s27, s25, -1
	s_cmp_eq_u32 s47, 12
	s_cselect_b32 s29, s17, s27
	s_cselect_b32 s28, s23, s26
	s_cselect_b32 s27, s15, s46
	s_cselect_b32 s26, s44, s45
	v_lshl_add_u64 v[220:221], s[24:25], 0, v[136:137]
	s_add_i32 m0, s34, 0xc000
	ds_read_b128 v[188:191], v153
	ds_read_b128 v[192:195], v153 offset:1024
	ds_read_b128 v[196:199], v153 offset:2048
	ds_read_b128 v[200:203], v153 offset:3072
	ds_read_b128 v[204:207], v153 offset:4096
	ds_read_b128 v[208:211], v153 offset:5120
	ds_read_b128 v[212:215], v153 offset:6144
	ds_read_b128 v[216:219], v153 offset:7168
	global_load_lds_dwordx4 v[220:221], off
	v_lshl_add_u64 v[220:221], s[24:25], 0, v[138:139]
	s_add_i32 m0, s34, 0xe000
	s_nop 0
	global_load_lds_dwordx4 v[220:221], off
	s_waitcnt vmcnt(8)
	s_waitcnt lgkmcnt(0)
	s_barrier
	s_waitcnt lgkmcnt(0)
	v_mfma_f32_16x16x32_bf16 v[124:127], v[144:147], v[188:191], v[124:127]
	v_mfma_f32_16x16x32_bf16 v[120:123], v[160:163], v[188:191], v[120:123]
	v_mfma_f32_16x16x32_bf16 v[108:111], v[144:147], v[196:199], v[108:111]
	v_mfma_f32_16x16x32_bf16 v[104:107], v[160:163], v[196:199], v[104:107]
	v_mfma_f32_16x16x32_bf16 v[92:95], v[144:147], v[204:207], v[92:95]
	v_mfma_f32_16x16x32_bf16 v[88:91], v[160:163], v[204:207], v[88:91]
	v_mfma_f32_16x16x32_bf16 v[76:79], v[144:147], v[212:215], v[76:79]
	v_mfma_f32_16x16x32_bf16 v[72:75], v[160:163], v[212:215], v[72:75]
	v_mfma_f32_16x16x32_bf16 v[124:127], v[156:159], v[192:195], v[124:127]
	v_mfma_f32_16x16x32_bf16 v[120:123], v[164:167], v[192:195], v[120:123]
	v_mfma_f32_16x16x32_bf16 v[108:111], v[156:159], v[200:203], v[108:111]
	v_mfma_f32_16x16x32_bf16 v[104:107], v[164:167], v[200:203], v[104:107]
	v_mfma_f32_16x16x32_bf16 v[92:95], v[156:159], v[208:211], v[92:95]
	v_mfma_f32_16x16x32_bf16 v[88:91], v[164:167], v[208:211], v[88:91]
	v_mfma_f32_16x16x32_bf16 v[76:79], v[156:159], v[216:219], v[76:79]
	v_mfma_f32_16x16x32_bf16 v[72:75], v[164:167], v[216:219], v[72:75]
	v_mfma_f32_16x16x32_bf16 v[116:119], v[168:171], v[188:191], v[116:119]
	v_mfma_f32_16x16x32_bf16 v[112:115], v[176:179], v[188:191], v[112:115]
	v_mfma_f32_16x16x32_bf16 v[100:103], v[168:171], v[196:199], v[100:103]
	v_mfma_f32_16x16x32_bf16 v[96:99], v[176:179], v[196:199], v[96:99]
	v_mfma_f32_16x16x32_bf16 v[84:87], v[168:171], v[204:207], v[84:87]
	v_mfma_f32_16x16x32_bf16 v[80:83], v[176:179], v[204:207], v[80:83]
	v_mfma_f32_16x16x32_bf16 v[68:71], v[168:171], v[212:215], v[68:71]
	v_mfma_f32_16x16x32_bf16 v[64:67], v[176:179], v[212:215], v[64:67]
	v_mfma_f32_16x16x32_bf16 v[116:119], v[172:175], v[192:195], v[116:119]
	v_mfma_f32_16x16x32_bf16 v[112:115], v[184:187], v[192:195], v[112:115]
	v_mfma_f32_16x16x32_bf16 v[100:103], v[172:175], v[200:203], v[100:103]
	v_mfma_f32_16x16x32_bf16 v[96:99], v[184:187], v[200:203], v[96:99]
	v_mfma_f32_16x16x32_bf16 v[84:87], v[172:175], v[208:211], v[84:87]
	v_mfma_f32_16x16x32_bf16 v[80:83], v[184:187], v[208:211], v[80:83]
	v_mfma_f32_16x16x32_bf16 v[68:71], v[172:175], v[216:219], v[68:71]
	v_mfma_f32_16x16x32_bf16 v[64:67], v[184:187], v[216:219], v[64:67]
	s_barrier
	s_add_i32 s50, s41, s33
	v_lshl_add_u64 v[220:221], s[26:27], 0, v[130:131]
	s_mov_b32 m0, s50
	ds_read_b128 v[188:191], v153 offset:16384
	ds_read_b128 v[192:195], v153 offset:17408
	ds_read_b128 v[196:199], v153 offset:18432
	ds_read_b128 v[200:203], v153 offset:19456
	ds_read_b128 v[204:207], v153 offset:20480
	ds_read_b128 v[208:211], v153 offset:21504
	ds_read_b128 v[212:215], v153 offset:22528
	ds_read_b128 v[216:219], v153 offset:23552
	global_load_lds_dwordx4 v[220:221], off
	s_add_i32 m0, s50, 0x2000
	s_add_u32 s50, s26, 0x40000
	v_lshl_add_u64 v[222:223], s[26:27], 0, v[134:135]
	s_addc_u32 s51, s27, 0
	s_add_i32 s52, s42, s33
	global_load_lds_dwordx4 v[222:223], off
	v_lshl_add_u64 v[224:225], s[50:51], 0, v[130:131]
	s_mov_b32 m0, s52
	global_load_lds_dwordx4 v[224:225], off
	v_lshl_add_u64 v[224:225], s[50:51], 0, v[134:135]
	s_add_i32 m0, s52, 0x2000
	s_nop 0
	global_load_lds_dwordx4 v[224:225], off
	s_waitcnt vmcnt(6)
	s_waitcnt lgkmcnt(0)
	s_barrier
	s_waitcnt lgkmcnt(0)
	v_mfma_f32_16x16x32_bf16 v[60:63], v[144:147], v[188:191], v[60:63]
	v_mfma_f32_16x16x32_bf16 v[56:59], v[160:163], v[188:191], v[56:59]
	v_mfma_f32_16x16x32_bf16 v[44:47], v[144:147], v[196:199], v[44:47]
	v_mfma_f32_16x16x32_bf16 v[40:43], v[160:163], v[196:199], v[40:43]
	v_mfma_f32_16x16x32_bf16 v[28:31], v[144:147], v[204:207], v[28:31]
	v_mfma_f32_16x16x32_bf16 v[24:27], v[160:163], v[204:207], v[24:27]
	v_mfma_f32_16x16x32_bf16 v[12:15], v[144:147], v[212:215], v[12:15]
	v_mfma_f32_16x16x32_bf16 v[8:11], v[160:163], v[212:215], v[8:11]
	v_mfma_f32_16x16x32_bf16 v[60:63], v[156:159], v[192:195], v[60:63]
	v_mfma_f32_16x16x32_bf16 v[56:59], v[164:167], v[192:195], v[56:59]
	v_mfma_f32_16x16x32_bf16 v[44:47], v[156:159], v[200:203], v[44:47]
	v_mfma_f32_16x16x32_bf16 v[40:43], v[164:167], v[200:203], v[40:43]
	v_mfma_f32_16x16x32_bf16 v[28:31], v[156:159], v[208:211], v[28:31]
	v_mfma_f32_16x16x32_bf16 v[24:27], v[164:167], v[208:211], v[24:27]
	v_mfma_f32_16x16x32_bf16 v[12:15], v[156:159], v[216:219], v[12:15]
	v_mfma_f32_16x16x32_bf16 v[8:11], v[164:167], v[216:219], v[8:11]
	v_mfma_f32_16x16x32_bf16 v[52:55], v[168:171], v[188:191], v[52:55]
	v_mfma_f32_16x16x32_bf16 v[48:51], v[176:179], v[188:191], v[48:51]
	v_mfma_f32_16x16x32_bf16 v[36:39], v[168:171], v[196:199], v[36:39]
	v_mfma_f32_16x16x32_bf16 v[32:35], v[176:179], v[196:199], v[32:35]
	v_mfma_f32_16x16x32_bf16 v[20:23], v[168:171], v[204:207], v[20:23]
	v_mfma_f32_16x16x32_bf16 v[16:19], v[176:179], v[204:207], v[16:19]
	v_mfma_f32_16x16x32_bf16 v[4:7], v[168:171], v[212:215], v[4:7]
	v_mfma_f32_16x16x32_bf16 v[0:3], v[176:179], v[212:215], v[0:3]
	v_mfma_f32_16x16x32_bf16 v[52:55], v[172:175], v[192:195], v[52:55]
	v_mfma_f32_16x16x32_bf16 v[48:51], v[184:187], v[192:195], v[48:51]
	v_mfma_f32_16x16x32_bf16 v[36:39], v[172:175], v[200:203], v[36:39]
	v_mfma_f32_16x16x32_bf16 v[32:35], v[184:187], v[200:203], v[32:35]
	v_mfma_f32_16x16x32_bf16 v[20:23], v[172:175], v[208:211], v[20:23]
	v_mfma_f32_16x16x32_bf16 v[16:19], v[184:187], v[208:211], v[16:19]
	v_mfma_f32_16x16x32_bf16 v[4:7], v[172:175], v[216:219], v[4:7]
	v_mfma_f32_16x16x32_bf16 v[0:3], v[184:187], v[216:219], v[0:3]
	s_barrier
	s_add_i32 s50, 0, 0x18000
	v_add_u32_e32 v155, s50, v149
	s_add_i32 s51, 0, 0x1c000
	ds_read_b128 v[144:147], v155
	ds_read_b128 v[156:159], v155 offset:1024
	ds_read_b128 v[160:163], v155 offset:2048
	ds_read_b128 v[164:167], v155 offset:3072
	v_add_u32_e32 v155, s51, v149
	ds_read_b128 v[168:171], v155
	ds_read_b128 v[172:175], v155 offset:1024
	ds_read_b128 v[176:179], v155 offset:2048
	ds_read_b128 v[184:187], v155 offset:3072
	v_lshl_add_u64 v[224:225], s[28:29], 0, v[128:129]
	s_mov_b32 m0, s34
	v_lshl_add_u64 v[226:227], s[28:29], 0, v[132:133]
	global_load_lds_dwordx4 v[224:225], off
	s_mov_b32 m0, s35
	s_nop 0
	global_load_lds_dwordx4 v[226:227], off
	s_add_u32 s28, s28, 0x40000
	s_addc_u32 s29, s29, 0
	s_mov_b32 m0, s36
	v_lshl_add_u64 v[228:229], s[28:29], 0, v[128:129]
	ds_read_b128 v[188:191], v153 offset:32768
	ds_read_b128 v[192:195], v153 offset:33792
	ds_read_b128 v[196:199], v153 offset:34816
	ds_read_b128 v[200:203], v153 offset:35840
	ds_read_b128 v[204:207], v153 offset:36864
	ds_read_b128 v[208:211], v153 offset:37888
	ds_read_b128 v[212:215], v153 offset:38912
	ds_read_b128 v[216:219], v153 offset:39936
	global_load_lds_dwordx4 v[228:229], off
	v_lshl_add_u64 v[228:229], s[28:29], 0, v[132:133]
	s_mov_b32 m0, s37
	s_nop 0
	global_load_lds_dwordx4 v[228:229], off
	s_waitcnt vmcnt(8)
	s_waitcnt lgkmcnt(0)
	s_barrier
	s_waitcnt lgkmcnt(0)
	v_mfma_f32_16x16x32_bf16 v[124:127], v[144:147], v[188:191], v[124:127]
	v_mfma_f32_16x16x32_bf16 v[120:123], v[160:163], v[188:191], v[120:123]
	v_mfma_f32_16x16x32_bf16 v[108:111], v[144:147], v[196:199], v[108:111]
	v_mfma_f32_16x16x32_bf16 v[104:107], v[160:163], v[196:199], v[104:107]
	v_mfma_f32_16x16x32_bf16 v[92:95], v[144:147], v[204:207], v[92:95]
	v_mfma_f32_16x16x32_bf16 v[88:91], v[160:163], v[204:207], v[88:91]
	v_mfma_f32_16x16x32_bf16 v[76:79], v[144:147], v[212:215], v[76:79]
	v_mfma_f32_16x16x32_bf16 v[72:75], v[160:163], v[212:215], v[72:75]
	v_mfma_f32_16x16x32_bf16 v[124:127], v[156:159], v[192:195], v[124:127]
	v_mfma_f32_16x16x32_bf16 v[120:123], v[164:167], v[192:195], v[120:123]
	v_mfma_f32_16x16x32_bf16 v[108:111], v[156:159], v[200:203], v[108:111]
	v_mfma_f32_16x16x32_bf16 v[104:107], v[164:167], v[200:203], v[104:107]
	v_mfma_f32_16x16x32_bf16 v[92:95], v[156:159], v[208:211], v[92:95]
	v_mfma_f32_16x16x32_bf16 v[88:91], v[164:167], v[208:211], v[88:91]
	v_mfma_f32_16x16x32_bf16 v[76:79], v[156:159], v[216:219], v[76:79]
	v_mfma_f32_16x16x32_bf16 v[72:75], v[164:167], v[216:219], v[72:75]
	v_mfma_f32_16x16x32_bf16 v[116:119], v[168:171], v[188:191], v[116:119]
	v_mfma_f32_16x16x32_bf16 v[112:115], v[176:179], v[188:191], v[112:115]
	v_mfma_f32_16x16x32_bf16 v[100:103], v[168:171], v[196:199], v[100:103]
	v_mfma_f32_16x16x32_bf16 v[96:99], v[176:179], v[196:199], v[96:99]
	v_mfma_f32_16x16x32_bf16 v[84:87], v[168:171], v[204:207], v[84:87]
	v_mfma_f32_16x16x32_bf16 v[80:83], v[176:179], v[204:207], v[80:83]
	v_mfma_f32_16x16x32_bf16 v[68:71], v[168:171], v[212:215], v[68:71]
	v_mfma_f32_16x16x32_bf16 v[64:67], v[176:179], v[212:215], v[64:67]
	v_mfma_f32_16x16x32_bf16 v[116:119], v[172:175], v[192:195], v[116:119]
	v_mfma_f32_16x16x32_bf16 v[112:115], v[184:187], v[192:195], v[112:115]
	v_mfma_f32_16x16x32_bf16 v[100:103], v[172:175], v[200:203], v[100:103]
	v_mfma_f32_16x16x32_bf16 v[96:99], v[184:187], v[200:203], v[96:99]
	v_mfma_f32_16x16x32_bf16 v[84:87], v[172:175], v[208:211], v[84:87]
	v_mfma_f32_16x16x32_bf16 v[80:83], v[184:187], v[208:211], v[80:83]
	v_mfma_f32_16x16x32_bf16 v[68:71], v[172:175], v[216:219], v[68:71]
	v_mfma_f32_16x16x32_bf16 v[64:67], v[184:187], v[216:219], v[64:67]
	s_barrier
	s_add_i32 s28, s50, s33
	v_lshl_add_u64 v[220:221], v[220:221], 0, s[10:11]
	s_mov_b32 m0, s28
	ds_read_b128 v[188:191], v153 offset:49152
	ds_read_b128 v[192:195], v153 offset:50176
	ds_read_b128 v[196:199], v153 offset:51200
	ds_read_b128 v[200:203], v153 offset:52224
	ds_read_b128 v[204:207], v153 offset:53248
	ds_read_b128 v[208:211], v153 offset:54272
	ds_read_b128 v[212:215], v153 offset:55296
	ds_read_b128 v[216:219], v153 offset:56320
	global_load_lds_dwordx4 v[220:221], off
	s_add_i32 m0, s28, 0x2000
	s_add_u32 s26, s26, 0x40080
	v_lshl_add_u64 v[220:221], v[222:223], 0, s[10:11]
	s_addc_u32 s27, s27, 0
	s_add_i32 s28, s51, s33
	global_load_lds_dwordx4 v[220:221], off
	v_lshl_add_u64 v[220:221], s[26:27], 0, v[130:131]
	s_mov_b32 m0, s28
	s_nop 0
	global_load_lds_dwordx4 v[220:221], off
	v_lshl_add_u64 v[220:221], s[26:27], 0, v[134:135]
	s_add_i32 m0, s28, 0x2000
	s_nop 0
	global_load_lds_dwordx4 v[220:221], off
	v_lshl_add_u64 v[220:221], v[224:225], 0, s[10:11]
	s_mov_b32 m0, s39
	s_nop 0
	global_load_lds_dwordx4 v[220:221], off
	v_lshl_add_u64 v[220:221], v[226:227], 0, s[10:11]
	s_mov_b32 m0, s40
	s_nop 0
	global_load_lds_dwordx4 v[220:221], off
	s_waitcnt vmcnt(6)
	s_waitcnt lgkmcnt(0)
	s_barrier
	s_waitcnt lgkmcnt(0)
	v_mfma_f32_16x16x32_bf16 v[60:63], v[144:147], v[188:191], v[60:63]
	v_mfma_f32_16x16x32_bf16 v[56:59], v[160:163], v[188:191], v[56:59]
	v_mfma_f32_16x16x32_bf16 v[44:47], v[144:147], v[196:199], v[44:47]
	v_mfma_f32_16x16x32_bf16 v[40:43], v[160:163], v[196:199], v[40:43]
	v_mfma_f32_16x16x32_bf16 v[28:31], v[144:147], v[204:207], v[28:31]
	v_mfma_f32_16x16x32_bf16 v[24:27], v[160:163], v[204:207], v[24:27]
	v_mfma_f32_16x16x32_bf16 v[12:15], v[144:147], v[212:215], v[12:15]
	v_mfma_f32_16x16x32_bf16 v[8:11], v[160:163], v[212:215], v[8:11]
	v_mfma_f32_16x16x32_bf16 v[60:63], v[156:159], v[192:195], v[60:63]
	v_mfma_f32_16x16x32_bf16 v[56:59], v[164:167], v[192:195], v[56:59]
	v_mfma_f32_16x16x32_bf16 v[44:47], v[156:159], v[200:203], v[44:47]
	v_mfma_f32_16x16x32_bf16 v[40:43], v[164:167], v[200:203], v[40:43]
	v_mfma_f32_16x16x32_bf16 v[28:31], v[156:159], v[208:211], v[28:31]
	v_mfma_f32_16x16x32_bf16 v[24:27], v[164:167], v[208:211], v[24:27]
	v_mfma_f32_16x16x32_bf16 v[12:15], v[156:159], v[216:219], v[12:15]
	v_mfma_f32_16x16x32_bf16 v[8:11], v[164:167], v[216:219], v[8:11]
	v_mfma_f32_16x16x32_bf16 v[52:55], v[168:171], v[188:191], v[52:55]
	v_mfma_f32_16x16x32_bf16 v[48:51], v[176:179], v[188:191], v[48:51]
	v_mfma_f32_16x16x32_bf16 v[36:39], v[168:171], v[196:199], v[36:39]
	v_mfma_f32_16x16x32_bf16 v[32:35], v[176:179], v[196:199], v[32:35]
	v_mfma_f32_16x16x32_bf16 v[20:23], v[168:171], v[204:207], v[20:23]
	v_mfma_f32_16x16x32_bf16 v[16:19], v[176:179], v[204:207], v[16:19]
	v_mfma_f32_16x16x32_bf16 v[4:7], v[168:171], v[212:215], v[4:7]
	v_mfma_f32_16x16x32_bf16 v[0:3], v[176:179], v[212:215], v[0:3]
	v_mfma_f32_16x16x32_bf16 v[52:55], v[172:175], v[192:195], v[52:55]
	v_mfma_f32_16x16x32_bf16 v[48:51], v[184:187], v[192:195], v[48:51]
	v_mfma_f32_16x16x32_bf16 v[36:39], v[172:175], v[200:203], v[36:39]
	v_mfma_f32_16x16x32_bf16 v[32:35], v[184:187], v[200:203], v[32:35]
	v_mfma_f32_16x16x32_bf16 v[20:23], v[172:175], v[208:211], v[20:23]
	v_mfma_f32_16x16x32_bf16 v[16:19], v[184:187], v[208:211], v[16:19]
	v_mfma_f32_16x16x32_bf16 v[4:7], v[172:175], v[216:219], v[4:7]
	v_mfma_f32_16x16x32_bf16 v[0:3], v[184:187], v[216:219], v[0:3]
	s_barrier
	s_add_i32 s47, s47, 2
	s_add_u32 s24, s24, 0x100
	s_addc_u32 s25, s25, 0
	s_add_u32 s45, s45, 0x100
	s_addc_u32 s46, s46, 0
	s_cmp_gt_u32 s47, 13
	s_cbranch_scc0 .LBB0_1291
	s_and_b64 vcc, exec, s[12:13]
	s_cbranch_vccz .LBB0_1294
	s_barrier

.LBB0_1379:
	ds_read_b128 v[154:157], v151
	ds_read_b128 v[158:161], v151 offset:1024
	ds_read_b128 v[162:165], v151 offset:2048
	ds_read_b128 v[166:169], v151 offset:3072
	ds_read_b128 v[170:173], v152
	ds_read_b128 v[174:177], v152 offset:1024
	ds_read_b128 v[184:187], v152 offset:2048
	ds_read_b128 v[188:191], v152 offset:3072
	s_add_u32 s22, s20, 0xfffc0080
	s_addc_u32 s23, s21, -1
	s_cmp_eq_u32 s46, 12
	s_cselect_b32 s25, s13, s23
	s_cselect_b32 s24, s42, s22
	s_cselect_b32 s23, s11, s45
	s_cselect_b32 s22, s43, s44
	v_lshl_add_u64 v[178:179], s[20:21], 0, v[136:137]
	s_add_i32 m0, s19, 0xc000
	ds_read_b128 v[192:195], v153
	ds_read_b128 v[196:199], v153 offset:1024
	ds_read_b128 v[200:203], v153 offset:2048
	ds_read_b128 v[204:207], v153 offset:3072
	ds_read_b128 v[208:211], v153 offset:4096
	ds_read_b128 v[212:215], v153 offset:5120
	ds_read_b128 v[216:219], v153 offset:6144
	ds_read_b128 v[220:223], v153 offset:7168
	global_load_lds_dwordx4 v[178:179], off
	v_lshl_add_u64 v[178:179], s[20:21], 0, v[138:139]
	s_add_i32 m0, s19, 0xe000
	s_nop 0
	global_load_lds_dwordx4 v[178:179], off
	s_waitcnt vmcnt(8)
	s_waitcnt lgkmcnt(0)
	s_barrier
	s_waitcnt lgkmcnt(0)
	v_mfma_f32_16x16x32_bf16 v[124:127], v[154:157], v[192:195], v[124:127]
	v_mfma_f32_16x16x32_bf16 v[116:119], v[162:165], v[192:195], v[116:119]
	v_mfma_f32_16x16x32_bf16 v[108:111], v[154:157], v[200:203], v[108:111]
	v_mfma_f32_16x16x32_bf16 v[100:103], v[162:165], v[200:203], v[100:103]
	v_mfma_f32_16x16x32_bf16 v[92:95], v[154:157], v[208:211], v[92:95]
	v_mfma_f32_16x16x32_bf16 v[84:87], v[162:165], v[208:211], v[84:87]
	v_mfma_f32_16x16x32_bf16 v[76:79], v[154:157], v[216:219], v[76:79]
	v_mfma_f32_16x16x32_bf16 v[68:71], v[162:165], v[216:219], v[68:71]
	v_mfma_f32_16x16x32_bf16 v[124:127], v[158:161], v[196:199], v[124:127]
	v_mfma_f32_16x16x32_bf16 v[116:119], v[166:169], v[196:199], v[116:119]
	v_mfma_f32_16x16x32_bf16 v[108:111], v[158:161], v[204:207], v[108:111]
	v_mfma_f32_16x16x32_bf16 v[100:103], v[166:169], v[204:207], v[100:103]
	v_mfma_f32_16x16x32_bf16 v[92:95], v[158:161], v[212:215], v[92:95]
	v_mfma_f32_16x16x32_bf16 v[84:87], v[166:169], v[212:215], v[84:87]
	v_mfma_f32_16x16x32_bf16 v[76:79], v[158:161], v[220:223], v[76:79]
	v_mfma_f32_16x16x32_bf16 v[68:71], v[166:169], v[220:223], v[68:71]
	v_mfma_f32_16x16x32_bf16 v[120:123], v[170:173], v[192:195], v[120:123]
	v_mfma_f32_16x16x32_bf16 v[112:115], v[184:187], v[192:195], v[112:115]
	v_mfma_f32_16x16x32_bf16 v[104:107], v[170:173], v[200:203], v[104:107]
	v_mfma_f32_16x16x32_bf16 v[96:99], v[184:187], v[200:203], v[96:99]
	v_mfma_f32_16x16x32_bf16 v[88:91], v[170:173], v[208:211], v[88:91]
	v_mfma_f32_16x16x32_bf16 v[80:83], v[184:187], v[208:211], v[80:83]
	v_mfma_f32_16x16x32_bf16 v[72:75], v[170:173], v[216:219], v[72:75]
	v_mfma_f32_16x16x32_bf16 v[64:67], v[184:187], v[216:219], v[64:67]
	v_mfma_f32_16x16x32_bf16 v[120:123], v[174:177], v[196:199], v[120:123]
	v_mfma_f32_16x16x32_bf16 v[112:115], v[188:191], v[196:199], v[112:115]
	v_mfma_f32_16x16x32_bf16 v[104:107], v[174:177], v[204:207], v[104:107]
	v_mfma_f32_16x16x32_bf16 v[96:99], v[188:191], v[204:207], v[96:99]
	v_mfma_f32_16x16x32_bf16 v[88:91], v[174:177], v[212:215], v[88:91]
	v_mfma_f32_16x16x32_bf16 v[80:83], v[188:191], v[212:215], v[80:83]
	v_mfma_f32_16x16x32_bf16 v[72:75], v[174:177], v[220:223], v[72:75]
	v_mfma_f32_16x16x32_bf16 v[64:67], v[188:191], v[220:223], v[64:67]
	s_barrier
	s_add_i32 s47, s36, s28
	v_lshl_add_u64 v[178:179], s[22:23], 0, v[132:133]
	s_mov_b32 m0, s47
	ds_read_b128 v[192:195], v153 offset:16384
	ds_read_b128 v[196:199], v153 offset:17408
	ds_read_b128 v[200:203], v153 offset:18432
	ds_read_b128 v[204:207], v153 offset:19456
	ds_read_b128 v[208:211], v153 offset:20480
	ds_read_b128 v[212:215], v153 offset:21504
	ds_read_b128 v[216:219], v153 offset:22528
	ds_read_b128 v[220:223], v153 offset:23552
	global_load_lds_dwordx4 v[178:179], off
	s_add_i32 m0, s47, 0x2000
	s_add_u32 s48, s22, 0x40000
	v_lshl_add_u64 v[224:225], s[22:23], 0, v[128:129]
	s_addc_u32 s49, s23, 0
	s_add_i32 s47, s37, s28
	global_load_lds_dwordx4 v[224:225], off
	v_lshl_add_u64 v[226:227], s[48:49], 0, v[132:133]
	s_mov_b32 m0, s47
	global_load_lds_dwordx4 v[226:227], off
	v_lshl_add_u64 v[226:227], s[48:49], 0, v[128:129]
	s_add_i32 m0, s47, 0x2000
	s_nop 0
	global_load_lds_dwordx4 v[226:227], off
	s_waitcnt vmcnt(6)
	s_waitcnt lgkmcnt(0)
	s_barrier
	s_waitcnt lgkmcnt(0)
	v_mfma_f32_16x16x32_bf16 v[60:63], v[154:157], v[192:195], v[60:63]
	v_mfma_f32_16x16x32_bf16 v[52:55], v[162:165], v[192:195], v[52:55]
	v_mfma_f32_16x16x32_bf16 v[44:47], v[154:157], v[200:203], v[44:47]
	v_mfma_f32_16x16x32_bf16 v[36:39], v[162:165], v[200:203], v[36:39]
	v_mfma_f32_16x16x32_bf16 v[28:31], v[154:157], v[208:211], v[28:31]
	v_mfma_f32_16x16x32_bf16 v[20:23], v[162:165], v[208:211], v[20:23]
	v_mfma_f32_16x16x32_bf16 v[12:15], v[154:157], v[216:219], v[12:15]
	v_mfma_f32_16x16x32_bf16 v[4:7], v[162:165], v[216:219], v[4:7]
	v_mfma_f32_16x16x32_bf16 v[60:63], v[158:161], v[196:199], v[60:63]
	v_mfma_f32_16x16x32_bf16 v[52:55], v[166:169], v[196:199], v[52:55]
	v_mfma_f32_16x16x32_bf16 v[44:47], v[158:161], v[204:207], v[44:47]
	v_mfma_f32_16x16x32_bf16 v[36:39], v[166:169], v[204:207], v[36:39]
	v_mfma_f32_16x16x32_bf16 v[28:31], v[158:161], v[212:215], v[28:31]
	v_mfma_f32_16x16x32_bf16 v[20:23], v[166:169], v[212:215], v[20:23]
	v_mfma_f32_16x16x32_bf16 v[12:15], v[158:161], v[220:223], v[12:15]
	v_mfma_f32_16x16x32_bf16 v[4:7], v[166:169], v[220:223], v[4:7]
	v_mfma_f32_16x16x32_bf16 v[56:59], v[170:173], v[192:195], v[56:59]
	v_mfma_f32_16x16x32_bf16 v[48:51], v[184:187], v[192:195], v[48:51]
	v_mfma_f32_16x16x32_bf16 v[40:43], v[170:173], v[200:203], v[40:43]
	v_mfma_f32_16x16x32_bf16 v[32:35], v[184:187], v[200:203], v[32:35]
	v_mfma_f32_16x16x32_bf16 v[24:27], v[170:173], v[208:211], v[24:27]
	v_mfma_f32_16x16x32_bf16 v[16:19], v[184:187], v[208:211], v[16:19]
	v_mfma_f32_16x16x32_bf16 v[8:11], v[170:173], v[216:219], v[8:11]
	v_mfma_f32_16x16x32_bf16 v[0:3], v[184:187], v[216:219], v[0:3]
	v_mfma_f32_16x16x32_bf16 v[56:59], v[174:177], v[196:199], v[56:59]
	v_mfma_f32_16x16x32_bf16 v[48:51], v[188:191], v[196:199], v[48:51]
	v_mfma_f32_16x16x32_bf16 v[40:43], v[174:177], v[204:207], v[40:43]
	v_mfma_f32_16x16x32_bf16 v[32:35], v[188:191], v[204:207], v[32:35]
	v_mfma_f32_16x16x32_bf16 v[24:27], v[174:177], v[212:215], v[24:27]
	v_mfma_f32_16x16x32_bf16 v[16:19], v[188:191], v[212:215], v[16:19]
	v_mfma_f32_16x16x32_bf16 v[8:11], v[174:177], v[220:223], v[8:11]
	v_mfma_f32_16x16x32_bf16 v[0:3], v[188:191], v[220:223], v[0:3]
	s_barrier
	s_add_i32 s47, 0, 0x18000
	s_add_i32 s48, 0, 0x1c000
	v_add_u32_e32 v166, s47, v145
	v_add_u32_e32 v180, s48, v145
	ds_read_b128 v[154:157], v166
	ds_read_b128 v[158:161], v166 offset:1024
	ds_read_b128 v[162:165], v166 offset:2048
	ds_read_b128 v[166:169], v166 offset:3072
	ds_read_b128 v[170:173], v180
	ds_read_b128 v[174:177], v180 offset:1024
	ds_read_b128 v[184:187], v180 offset:2048
	ds_read_b128 v[188:191], v180 offset:3072
	v_lshl_add_u64 v[226:227], s[24:25], 0, v[134:135]
	s_mov_b32 m0, s19
	v_lshl_add_u64 v[228:229], s[24:25], 0, v[130:131]
	global_load_lds_dwordx4 v[226:227], off
	s_mov_b32 m0, s30
	s_nop 0
	global_load_lds_dwordx4 v[228:229], off
	s_add_u32 s24, s24, 0x40000
	s_addc_u32 s25, s25, 0
	s_mov_b32 m0, s31
	v_lshl_add_u64 v[230:231], s[24:25], 0, v[134:135]
	ds_read_b128 v[192:195], v153 offset:32768
	ds_read_b128 v[196:199], v153 offset:33792
	ds_read_b128 v[200:203], v153 offset:34816
	ds_read_b128 v[204:207], v153 offset:35840
	ds_read_b128 v[208:211], v153 offset:36864
	ds_read_b128 v[212:215], v153 offset:37888
	ds_read_b128 v[216:219], v153 offset:38912
	ds_read_b128 v[220:223], v153 offset:39936
	global_load_lds_dwordx4 v[230:231], off
	v_lshl_add_u64 v[230:231], s[24:25], 0, v[130:131]
	s_mov_b32 m0, s33
	s_nop 0
	global_load_lds_dwordx4 v[230:231], off
	s_waitcnt vmcnt(8)
	s_waitcnt lgkmcnt(0)
	s_barrier
	s_waitcnt lgkmcnt(0)
	v_mfma_f32_16x16x32_bf16 v[124:127], v[154:157], v[192:195], v[124:127]
	v_mfma_f32_16x16x32_bf16 v[116:119], v[162:165], v[192:195], v[116:119]
	v_mfma_f32_16x16x32_bf16 v[108:111], v[154:157], v[200:203], v[108:111]
	v_mfma_f32_16x16x32_bf16 v[100:103], v[162:165], v[200:203], v[100:103]
	v_mfma_f32_16x16x32_bf16 v[92:95], v[154:157], v[208:211], v[92:95]
	v_mfma_f32_16x16x32_bf16 v[84:87], v[162:165], v[208:211], v[84:87]
	v_mfma_f32_16x16x32_bf16 v[76:79], v[154:157], v[216:219], v[76:79]
	v_mfma_f32_16x16x32_bf16 v[68:71], v[162:165], v[216:219], v[68:71]
	v_mfma_f32_16x16x32_bf16 v[124:127], v[158:161], v[196:199], v[124:127]
	v_mfma_f32_16x16x32_bf16 v[116:119], v[166:169], v[196:199], v[116:119]
	v_mfma_f32_16x16x32_bf16 v[108:111], v[158:161], v[204:207], v[108:111]
	v_mfma_f32_16x16x32_bf16 v[100:103], v[166:169], v[204:207], v[100:103]
	v_mfma_f32_16x16x32_bf16 v[92:95], v[158:161], v[212:215], v[92:95]
	v_mfma_f32_16x16x32_bf16 v[84:87], v[166:169], v[212:215], v[84:87]
	v_mfma_f32_16x16x32_bf16 v[76:79], v[158:161], v[220:223], v[76:79]
	v_mfma_f32_16x16x32_bf16 v[68:71], v[166:169], v[220:223], v[68:71]
	v_mfma_f32_16x16x32_bf16 v[120:123], v[170:173], v[192:195], v[120:123]
	v_mfma_f32_16x16x32_bf16 v[112:115], v[184:187], v[192:195], v[112:115]
	v_mfma_f32_16x16x32_bf16 v[104:107], v[170:173], v[200:203], v[104:107]
	v_mfma_f32_16x16x32_bf16 v[96:99], v[184:187], v[200:203], v[96:99]
	v_mfma_f32_16x16x32_bf16 v[88:91], v[170:173], v[208:211], v[88:91]
	v_mfma_f32_16x16x32_bf16 v[80:83], v[184:187], v[208:211], v[80:83]
	v_mfma_f32_16x16x32_bf16 v[72:75], v[170:173], v[216:219], v[72:75]
	v_mfma_f32_16x16x32_bf16 v[64:67], v[184:187], v[216:219], v[64:67]
	v_mfma_f32_16x16x32_bf16 v[120:123], v[174:177], v[196:199], v[120:123]
	v_mfma_f32_16x16x32_bf16 v[112:115], v[188:191], v[196:199], v[112:115]
	v_mfma_f32_16x16x32_bf16 v[104:107], v[174:177], v[204:207], v[104:107]
	v_mfma_f32_16x16x32_bf16 v[96:99], v[188:191], v[204:207], v[96:99]
	v_mfma_f32_16x16x32_bf16 v[88:91], v[174:177], v[212:215], v[88:91]
	v_mfma_f32_16x16x32_bf16 v[80:83], v[188:191], v[212:215], v[80:83]
	v_mfma_f32_16x16x32_bf16 v[72:75], v[174:177], v[220:223], v[72:75]
	v_mfma_f32_16x16x32_bf16 v[64:67], v[188:191], v[220:223], v[64:67]
	s_barrier
	s_add_i32 s24, s47, s28
	v_lshl_add_u64 v[178:179], v[178:179], 0, s[6:7]
	s_mov_b32 m0, s24
	ds_read_b128 v[192:195], v153 offset:49152
	ds_read_b128 v[196:199], v153 offset:50176
	ds_read_b128 v[200:203], v153 offset:51200
	ds_read_b128 v[204:207], v153 offset:52224
	ds_read_b128 v[208:211], v153 offset:53248
	ds_read_b128 v[212:215], v153 offset:54272
	ds_read_b128 v[216:219], v153 offset:55296
	ds_read_b128 v[220:223], v153 offset:56320
	global_load_lds_dwordx4 v[178:179], off
	s_add_i32 m0, s24, 0x2000
	s_add_u32 s22, s22, 0x40080
	v_lshl_add_u64 v[178:179], v[224:225], 0, s[6:7]
	s_addc_u32 s23, s23, 0
	s_add_i32 s24, s48, s28
	global_load_lds_dwordx4 v[178:179], off
	v_lshl_add_u64 v[178:179], s[22:23], 0, v[132:133]
	s_mov_b32 m0, s24
	s_nop 0
	global_load_lds_dwordx4 v[178:179], off
	v_lshl_add_u64 v[178:179], s[22:23], 0, v[128:129]
	s_add_i32 m0, s24, 0x2000
	s_nop 0
	global_load_lds_dwordx4 v[178:179], off
	v_lshl_add_u64 v[178:179], v[226:227], 0, s[6:7]
	s_mov_b32 m0, s34
	s_nop 0
	global_load_lds_dwordx4 v[178:179], off
	v_lshl_add_u64 v[178:179], v[228:229], 0, s[6:7]
	s_mov_b32 m0, s35
	s_nop 0
	global_load_lds_dwordx4 v[178:179], off
	s_waitcnt vmcnt(6)
	s_waitcnt lgkmcnt(0)
	s_barrier
	s_waitcnt lgkmcnt(0)
	v_mfma_f32_16x16x32_bf16 v[60:63], v[154:157], v[192:195], v[60:63]
	v_mfma_f32_16x16x32_bf16 v[52:55], v[162:165], v[192:195], v[52:55]
	v_mfma_f32_16x16x32_bf16 v[44:47], v[154:157], v[200:203], v[44:47]
	v_mfma_f32_16x16x32_bf16 v[36:39], v[162:165], v[200:203], v[36:39]
	v_mfma_f32_16x16x32_bf16 v[28:31], v[154:157], v[208:211], v[28:31]
	v_mfma_f32_16x16x32_bf16 v[20:23], v[162:165], v[208:211], v[20:23]
	v_mfma_f32_16x16x32_bf16 v[12:15], v[154:157], v[216:219], v[12:15]
	v_mfma_f32_16x16x32_bf16 v[4:7], v[162:165], v[216:219], v[4:7]
	v_mfma_f32_16x16x32_bf16 v[60:63], v[158:161], v[196:199], v[60:63]
	v_mfma_f32_16x16x32_bf16 v[52:55], v[166:169], v[196:199], v[52:55]
	v_mfma_f32_16x16x32_bf16 v[44:47], v[158:161], v[204:207], v[44:47]
	v_mfma_f32_16x16x32_bf16 v[36:39], v[166:169], v[204:207], v[36:39]
	v_mfma_f32_16x16x32_bf16 v[28:31], v[158:161], v[212:215], v[28:31]
	v_mfma_f32_16x16x32_bf16 v[20:23], v[166:169], v[212:215], v[20:23]
	v_mfma_f32_16x16x32_bf16 v[12:15], v[158:161], v[220:223], v[12:15]
	v_mfma_f32_16x16x32_bf16 v[4:7], v[166:169], v[220:223], v[4:7]
	v_mfma_f32_16x16x32_bf16 v[56:59], v[170:173], v[192:195], v[56:59]
	v_mfma_f32_16x16x32_bf16 v[48:51], v[184:187], v[192:195], v[48:51]
	v_mfma_f32_16x16x32_bf16 v[40:43], v[170:173], v[200:203], v[40:43]
	v_mfma_f32_16x16x32_bf16 v[32:35], v[184:187], v[200:203], v[32:35]
	v_mfma_f32_16x16x32_bf16 v[24:27], v[170:173], v[208:211], v[24:27]
	v_mfma_f32_16x16x32_bf16 v[16:19], v[184:187], v[208:211], v[16:19]
	v_mfma_f32_16x16x32_bf16 v[8:11], v[170:173], v[216:219], v[8:11]
	v_mfma_f32_16x16x32_bf16 v[0:3], v[184:187], v[216:219], v[0:3]
	v_mfma_f32_16x16x32_bf16 v[56:59], v[174:177], v[196:199], v[56:59]
	v_mfma_f32_16x16x32_bf16 v[48:51], v[188:191], v[196:199], v[48:51]
	v_mfma_f32_16x16x32_bf16 v[40:43], v[174:177], v[204:207], v[40:43]
	v_mfma_f32_16x16x32_bf16 v[32:35], v[188:191], v[204:207], v[32:35]
	v_mfma_f32_16x16x32_bf16 v[24:27], v[174:177], v[212:215], v[24:27]
	v_mfma_f32_16x16x32_bf16 v[16:19], v[188:191], v[212:215], v[16:19]
	v_mfma_f32_16x16x32_bf16 v[8:11], v[174:177], v[220:223], v[8:11]
	v_mfma_f32_16x16x32_bf16 v[0:3], v[188:191], v[220:223], v[0:3]
	s_barrier
	s_add_i32 s46, s46, 2
	s_add_u32 s20, s20, 0x100
	s_addc_u32 s21, s21, 0
	s_add_u32 s44, s44, 0x100
	s_addc_u32 s45, s45, 0
	s_cmp_gt_u32 s46, 13
	s_cbranch_scc0 .LBB0_1379
	s_and_b64 vcc, exec, s[8:9]
	s_cbranch_vccz .LBB0_1382
	s_barrier

.LBB0_1461:
	ds_read_b128 v[144:147], v151
	ds_read_b128 v[156:159], v151 offset:1024
	ds_read_b128 v[160:163], v151 offset:2048
	ds_read_b128 v[164:167], v151 offset:3072
	ds_read_b128 v[168:171], v152
	ds_read_b128 v[172:175], v152 offset:1024
	ds_read_b128 v[176:179], v152 offset:2048
	ds_read_b128 v[182:185], v152 offset:3072
	s_add_u32 s20, s18, 0x100
	s_addc_u32 s21, s19, 0
	s_cmp_eq_u32 s45, 40
	s_cselect_b32 s25, s7, s21
	s_cselect_b32 s24, s6, s20
	s_cselect_b32 s23, s17, s44
	s_cselect_b32 s22, s16, s43
	v_lshl_add_u64 v[218:219], s[18:19], 0, v[136:137]
	s_add_i32 m0, s29, 0xc000
	ds_read_b128 v[186:189], v153
	ds_read_b128 v[190:193], v153 offset:1024
	ds_read_b128 v[194:197], v153 offset:2048
	ds_read_b128 v[198:201], v153 offset:3072
	ds_read_b128 v[202:205], v153 offset:4096
	ds_read_b128 v[206:209], v153 offset:5120
	ds_read_b128 v[210:213], v153 offset:6144
	ds_read_b128 v[214:217], v153 offset:7168
	global_load_lds_dwordx4 v[218:219], off
	v_lshl_add_u64 v[218:219], s[18:19], 0, v[138:139]
	s_add_i32 m0, s29, 0xe000
	s_nop 0
	global_load_lds_dwordx4 v[218:219], off
	s_waitcnt vmcnt(8)
	s_waitcnt lgkmcnt(0)
	s_barrier
	s_waitcnt lgkmcnt(0)
	v_mfma_f32_16x16x32_bf16 v[124:127], v[144:147], v[186:189], v[124:127]
	v_mfma_f32_16x16x32_bf16 v[120:123], v[160:163], v[186:189], v[120:123]
	v_mfma_f32_16x16x32_bf16 v[108:111], v[144:147], v[194:197], v[108:111]
	v_mfma_f32_16x16x32_bf16 v[104:107], v[160:163], v[194:197], v[104:107]
	v_mfma_f32_16x16x32_bf16 v[92:95], v[144:147], v[202:205], v[92:95]
	v_mfma_f32_16x16x32_bf16 v[88:91], v[160:163], v[202:205], v[88:91]
	v_mfma_f32_16x16x32_bf16 v[76:79], v[144:147], v[210:213], v[76:79]
	v_mfma_f32_16x16x32_bf16 v[72:75], v[160:163], v[210:213], v[72:75]
	v_mfma_f32_16x16x32_bf16 v[124:127], v[156:159], v[190:193], v[124:127]
	v_mfma_f32_16x16x32_bf16 v[120:123], v[164:167], v[190:193], v[120:123]
	v_mfma_f32_16x16x32_bf16 v[108:111], v[156:159], v[198:201], v[108:111]
	v_mfma_f32_16x16x32_bf16 v[104:107], v[164:167], v[198:201], v[104:107]
	v_mfma_f32_16x16x32_bf16 v[92:95], v[156:159], v[206:209], v[92:95]
	v_mfma_f32_16x16x32_bf16 v[88:91], v[164:167], v[206:209], v[88:91]
	v_mfma_f32_16x16x32_bf16 v[76:79], v[156:159], v[214:217], v[76:79]
	v_mfma_f32_16x16x32_bf16 v[72:75], v[164:167], v[214:217], v[72:75]
	v_mfma_f32_16x16x32_bf16 v[116:119], v[168:171], v[186:189], v[116:119]
	v_mfma_f32_16x16x32_bf16 v[112:115], v[176:179], v[186:189], v[112:115]
	v_mfma_f32_16x16x32_bf16 v[100:103], v[168:171], v[194:197], v[100:103]
	v_mfma_f32_16x16x32_bf16 v[96:99], v[176:179], v[194:197], v[96:99]
	v_mfma_f32_16x16x32_bf16 v[84:87], v[168:171], v[202:205], v[84:87]
	v_mfma_f32_16x16x32_bf16 v[80:83], v[176:179], v[202:205], v[80:83]
	v_mfma_f32_16x16x32_bf16 v[68:71], v[168:171], v[210:213], v[68:71]
	v_mfma_f32_16x16x32_bf16 v[64:67], v[176:179], v[210:213], v[64:67]
	v_mfma_f32_16x16x32_bf16 v[116:119], v[172:175], v[190:193], v[116:119]
	v_mfma_f32_16x16x32_bf16 v[112:115], v[182:185], v[190:193], v[112:115]
	v_mfma_f32_16x16x32_bf16 v[100:103], v[172:175], v[198:201], v[100:103]
	v_mfma_f32_16x16x32_bf16 v[96:99], v[182:185], v[198:201], v[96:99]
	v_mfma_f32_16x16x32_bf16 v[84:87], v[172:175], v[206:209], v[84:87]
	v_mfma_f32_16x16x32_bf16 v[80:83], v[182:185], v[206:209], v[80:83]
	v_mfma_f32_16x16x32_bf16 v[68:71], v[172:175], v[214:217], v[68:71]
	v_mfma_f32_16x16x32_bf16 v[64:67], v[182:185], v[214:217], v[64:67]
	s_barrier
	s_add_i32 s18, s37, s28
	v_lshl_add_u64 v[218:219], s[22:23], 0, v[130:131]
	s_mov_b32 m0, s18
	ds_read_b128 v[186:189], v153 offset:16384
	ds_read_b128 v[190:193], v153 offset:17408
	ds_read_b128 v[194:197], v153 offset:18432
	ds_read_b128 v[198:201], v153 offset:19456
	ds_read_b128 v[202:205], v153 offset:20480
	ds_read_b128 v[206:209], v153 offset:21504
	ds_read_b128 v[210:213], v153 offset:22528
	ds_read_b128 v[214:217], v153 offset:23552
	global_load_lds_dwordx4 v[218:219], off
	s_add_i32 m0, s18, 0x2000
	s_add_u32 s18, s22, 0xb0000
	v_lshl_add_u64 v[220:221], s[22:23], 0, v[134:135]
	s_addc_u32 s19, s23, 0
	s_add_i32 s46, s38, s28
	global_load_lds_dwordx4 v[220:221], off
	v_lshl_add_u64 v[222:223], s[18:19], 0, v[130:131]
	s_mov_b32 m0, s46
	global_load_lds_dwordx4 v[222:223], off
	v_lshl_add_u64 v[222:223], s[18:19], 0, v[134:135]
	s_add_i32 m0, s46, 0x2000
	s_nop 0
	global_load_lds_dwordx4 v[222:223], off
	s_waitcnt vmcnt(6)
	s_waitcnt lgkmcnt(0)
	s_barrier
	s_waitcnt lgkmcnt(0)
	v_mfma_f32_16x16x32_bf16 v[60:63], v[144:147], v[186:189], v[60:63]
	v_mfma_f32_16x16x32_bf16 v[56:59], v[160:163], v[186:189], v[56:59]
	v_mfma_f32_16x16x32_bf16 v[44:47], v[144:147], v[194:197], v[44:47]
	v_mfma_f32_16x16x32_bf16 v[40:43], v[160:163], v[194:197], v[40:43]
	v_mfma_f32_16x16x32_bf16 v[28:31], v[144:147], v[202:205], v[28:31]
	v_mfma_f32_16x16x32_bf16 v[24:27], v[160:163], v[202:205], v[24:27]
	v_mfma_f32_16x16x32_bf16 v[12:15], v[144:147], v[210:213], v[12:15]
	v_mfma_f32_16x16x32_bf16 v[8:11], v[160:163], v[210:213], v[8:11]
	v_mfma_f32_16x16x32_bf16 v[60:63], v[156:159], v[190:193], v[60:63]
	v_mfma_f32_16x16x32_bf16 v[56:59], v[164:167], v[190:193], v[56:59]
	v_mfma_f32_16x16x32_bf16 v[44:47], v[156:159], v[198:201], v[44:47]
	v_mfma_f32_16x16x32_bf16 v[40:43], v[164:167], v[198:201], v[40:43]
	v_mfma_f32_16x16x32_bf16 v[28:31], v[156:159], v[206:209], v[28:31]
	v_mfma_f32_16x16x32_bf16 v[24:27], v[164:167], v[206:209], v[24:27]
	v_mfma_f32_16x16x32_bf16 v[12:15], v[156:159], v[214:217], v[12:15]
	v_mfma_f32_16x16x32_bf16 v[8:11], v[164:167], v[214:217], v[8:11]
	v_mfma_f32_16x16x32_bf16 v[52:55], v[168:171], v[186:189], v[52:55]
	v_mfma_f32_16x16x32_bf16 v[48:51], v[176:179], v[186:189], v[48:51]
	v_mfma_f32_16x16x32_bf16 v[36:39], v[168:171], v[194:197], v[36:39]
	v_mfma_f32_16x16x32_bf16 v[32:35], v[176:179], v[194:197], v[32:35]
	v_mfma_f32_16x16x32_bf16 v[20:23], v[168:171], v[202:205], v[20:23]
	v_mfma_f32_16x16x32_bf16 v[16:19], v[176:179], v[202:205], v[16:19]
	v_mfma_f32_16x16x32_bf16 v[4:7], v[168:171], v[210:213], v[4:7]
	v_mfma_f32_16x16x32_bf16 v[0:3], v[176:179], v[210:213], v[0:3]
	v_mfma_f32_16x16x32_bf16 v[52:55], v[172:175], v[190:193], v[52:55]
	v_mfma_f32_16x16x32_bf16 v[48:51], v[182:185], v[190:193], v[48:51]
	v_mfma_f32_16x16x32_bf16 v[36:39], v[172:175], v[198:201], v[36:39]
	v_mfma_f32_16x16x32_bf16 v[32:35], v[182:185], v[198:201], v[32:35]
	v_mfma_f32_16x16x32_bf16 v[20:23], v[172:175], v[206:209], v[20:23]
	v_mfma_f32_16x16x32_bf16 v[16:19], v[182:185], v[206:209], v[16:19]
	v_mfma_f32_16x16x32_bf16 v[4:7], v[172:175], v[214:217], v[4:7]
	v_mfma_f32_16x16x32_bf16 v[0:3], v[182:185], v[214:217], v[0:3]
	s_barrier
	s_add_i32 s46, 0, 0x18000
	v_add_u32_e32 v155, s46, v149
	s_add_i32 s47, 0, 0x1c000
	ds_read_b128 v[144:147], v155
	ds_read_b128 v[156:159], v155 offset:1024
	ds_read_b128 v[160:163], v155 offset:2048
	ds_read_b128 v[164:167], v155 offset:3072
	v_add_u32_e32 v155, s47, v149
	ds_read_b128 v[168:171], v155
	ds_read_b128 v[172:175], v155 offset:1024
	ds_read_b128 v[176:179], v155 offset:2048
	ds_read_b128 v[182:185], v155 offset:3072
	s_add_u32 s18, s24, 0xb0000
	s_addc_u32 s19, s25, 0
	v_lshl_add_u64 v[222:223], s[24:25], 0, v[128:129]
	s_mov_b32 m0, s29
	v_lshl_add_u64 v[224:225], s[24:25], 0, v[132:133]
	global_load_lds_dwordx4 v[222:223], off
	s_mov_b32 m0, s30
	s_nop 0
	global_load_lds_dwordx4 v[224:225], off
	s_mov_b32 m0, s31
	v_lshl_add_u64 v[226:227], s[18:19], 0, v[128:129]
	ds_read_b128 v[186:189], v153 offset:32768
	ds_read_b128 v[190:193], v153 offset:33792
	ds_read_b128 v[194:197], v153 offset:34816
	ds_read_b128 v[198:201], v153 offset:35840
	ds_read_b128 v[202:205], v153 offset:36864
	ds_read_b128 v[206:209], v153 offset:37888
	ds_read_b128 v[210:213], v153 offset:38912
	ds_read_b128 v[214:217], v153 offset:39936
	global_load_lds_dwordx4 v[226:227], off
	v_lshl_add_u64 v[226:227], s[18:19], 0, v[132:133]
	s_mov_b32 m0, s33
	s_nop 0
	global_load_lds_dwordx4 v[226:227], off
	s_waitcnt vmcnt(8)
	s_waitcnt lgkmcnt(0)
	s_barrier
	s_waitcnt lgkmcnt(0)
	v_mfma_f32_16x16x32_bf16 v[124:127], v[144:147], v[186:189], v[124:127]
	v_mfma_f32_16x16x32_bf16 v[120:123], v[160:163], v[186:189], v[120:123]
	v_mfma_f32_16x16x32_bf16 v[108:111], v[144:147], v[194:197], v[108:111]
	v_mfma_f32_16x16x32_bf16 v[104:107], v[160:163], v[194:197], v[104:107]
	v_mfma_f32_16x16x32_bf16 v[92:95], v[144:147], v[202:205], v[92:95]
	v_mfma_f32_16x16x32_bf16 v[88:91], v[160:163], v[202:205], v[88:91]
	v_mfma_f32_16x16x32_bf16 v[76:79], v[144:147], v[210:213], v[76:79]
	v_mfma_f32_16x16x32_bf16 v[72:75], v[160:163], v[210:213], v[72:75]
	v_mfma_f32_16x16x32_bf16 v[124:127], v[156:159], v[190:193], v[124:127]
	v_mfma_f32_16x16x32_bf16 v[120:123], v[164:167], v[190:193], v[120:123]
	v_mfma_f32_16x16x32_bf16 v[108:111], v[156:159], v[198:201], v[108:111]
	v_mfma_f32_16x16x32_bf16 v[104:107], v[164:167], v[198:201], v[104:107]
	v_mfma_f32_16x16x32_bf16 v[92:95], v[156:159], v[206:209], v[92:95]
	v_mfma_f32_16x16x32_bf16 v[88:91], v[164:167], v[206:209], v[88:91]
	v_mfma_f32_16x16x32_bf16 v[76:79], v[156:159], v[214:217], v[76:79]
	v_mfma_f32_16x16x32_bf16 v[72:75], v[164:167], v[214:217], v[72:75]
	v_mfma_f32_16x16x32_bf16 v[116:119], v[168:171], v[186:189], v[116:119]
	v_mfma_f32_16x16x32_bf16 v[112:115], v[176:179], v[186:189], v[112:115]
	v_mfma_f32_16x16x32_bf16 v[100:103], v[168:171], v[194:197], v[100:103]
	v_mfma_f32_16x16x32_bf16 v[96:99], v[176:179], v[194:197], v[96:99]
	v_mfma_f32_16x16x32_bf16 v[84:87], v[168:171], v[202:205], v[84:87]
	v_mfma_f32_16x16x32_bf16 v[80:83], v[176:179], v[202:205], v[80:83]
	v_mfma_f32_16x16x32_bf16 v[68:71], v[168:171], v[210:213], v[68:71]
	v_mfma_f32_16x16x32_bf16 v[64:67], v[176:179], v[210:213], v[64:67]
	v_mfma_f32_16x16x32_bf16 v[116:119], v[172:175], v[190:193], v[116:119]
	v_mfma_f32_16x16x32_bf16 v[112:115], v[182:185], v[190:193], v[112:115]
	v_mfma_f32_16x16x32_bf16 v[100:103], v[172:175], v[198:201], v[100:103]
	v_mfma_f32_16x16x32_bf16 v[96:99], v[182:185], v[198:201], v[96:99]
	v_mfma_f32_16x16x32_bf16 v[84:87], v[172:175], v[206:209], v[84:87]
	v_mfma_f32_16x16x32_bf16 v[80:83], v[182:185], v[206:209], v[80:83]
	v_mfma_f32_16x16x32_bf16 v[68:71], v[172:175], v[214:217], v[68:71]
	v_mfma_f32_16x16x32_bf16 v[64:67], v[182:185], v[214:217], v[64:67]
	s_barrier
	s_add_i32 s18, s46, s28
	v_lshl_add_u64 v[218:219], v[218:219], 0, s[12:13]
	s_mov_b32 m0, s18
	ds_read_b128 v[186:189], v153 offset:49152
	ds_read_b128 v[190:193], v153 offset:50176
	ds_read_b128 v[194:197], v153 offset:51200
	ds_read_b128 v[198:201], v153 offset:52224
	ds_read_b128 v[202:205], v153 offset:53248
	ds_read_b128 v[206:209], v153 offset:54272
	ds_read_b128 v[210:213], v153 offset:55296
	ds_read_b128 v[214:217], v153 offset:56320
	global_load_lds_dwordx4 v[218:219], off
	s_add_i32 m0, s18, 0x2000
	s_add_u32 s18, s22, 0xb0080
	v_lshl_add_u64 v[218:219], v[220:221], 0, s[12:13]
	s_addc_u32 s19, s23, 0
	s_add_i32 s22, s47, s28
	global_load_lds_dwordx4 v[218:219], off
	v_lshl_add_u64 v[218:219], s[18:19], 0, v[130:131]
	s_mov_b32 m0, s22
	s_nop 0
	global_load_lds_dwordx4 v[218:219], off
	v_lshl_add_u64 v[218:219], s[18:19], 0, v[134:135]
	s_add_i32 m0, s22, 0x2000
	s_nop 0
	global_load_lds_dwordx4 v[218:219], off
	v_lshl_add_u64 v[218:219], v[222:223], 0, s[12:13]
	s_mov_b32 m0, s35
	s_nop 0
	global_load_lds_dwordx4 v[218:219], off
	v_lshl_add_u64 v[218:219], v[224:225], 0, s[12:13]
	s_mov_b32 m0, s36
	s_nop 0
	global_load_lds_dwordx4 v[218:219], off
	s_waitcnt vmcnt(6)
	s_waitcnt lgkmcnt(0)
	s_barrier
	s_waitcnt lgkmcnt(0)
	v_mfma_f32_16x16x32_bf16 v[60:63], v[144:147], v[186:189], v[60:63]
	v_mfma_f32_16x16x32_bf16 v[56:59], v[160:163], v[186:189], v[56:59]
	v_mfma_f32_16x16x32_bf16 v[44:47], v[144:147], v[194:197], v[44:47]
	v_mfma_f32_16x16x32_bf16 v[40:43], v[160:163], v[194:197], v[40:43]
	v_mfma_f32_16x16x32_bf16 v[28:31], v[144:147], v[202:205], v[28:31]
	v_mfma_f32_16x16x32_bf16 v[24:27], v[160:163], v[202:205], v[24:27]
	v_mfma_f32_16x16x32_bf16 v[12:15], v[144:147], v[210:213], v[12:15]
	v_mfma_f32_16x16x32_bf16 v[8:11], v[160:163], v[210:213], v[8:11]
	v_mfma_f32_16x16x32_bf16 v[60:63], v[156:159], v[190:193], v[60:63]
	v_mfma_f32_16x16x32_bf16 v[56:59], v[164:167], v[190:193], v[56:59]
	v_mfma_f32_16x16x32_bf16 v[44:47], v[156:159], v[198:201], v[44:47]
	v_mfma_f32_16x16x32_bf16 v[40:43], v[164:167], v[198:201], v[40:43]
	v_mfma_f32_16x16x32_bf16 v[28:31], v[156:159], v[206:209], v[28:31]
	v_mfma_f32_16x16x32_bf16 v[24:27], v[164:167], v[206:209], v[24:27]
	v_mfma_f32_16x16x32_bf16 v[12:15], v[156:159], v[214:217], v[12:15]
	v_mfma_f32_16x16x32_bf16 v[8:11], v[164:167], v[214:217], v[8:11]
	v_mfma_f32_16x16x32_bf16 v[52:55], v[168:171], v[186:189], v[52:55]
	v_mfma_f32_16x16x32_bf16 v[48:51], v[176:179], v[186:189], v[48:51]
	v_mfma_f32_16x16x32_bf16 v[36:39], v[168:171], v[194:197], v[36:39]
	v_mfma_f32_16x16x32_bf16 v[32:35], v[176:179], v[194:197], v[32:35]
	v_mfma_f32_16x16x32_bf16 v[20:23], v[168:171], v[202:205], v[20:23]
	v_mfma_f32_16x16x32_bf16 v[16:19], v[176:179], v[202:205], v[16:19]
	v_mfma_f32_16x16x32_bf16 v[4:7], v[168:171], v[210:213], v[4:7]
	v_mfma_f32_16x16x32_bf16 v[0:3], v[176:179], v[210:213], v[0:3]
	v_mfma_f32_16x16x32_bf16 v[52:55], v[172:175], v[190:193], v[52:55]
	v_mfma_f32_16x16x32_bf16 v[48:51], v[182:185], v[190:193], v[48:51]
	v_mfma_f32_16x16x32_bf16 v[36:39], v[172:175], v[198:201], v[36:39]
	v_mfma_f32_16x16x32_bf16 v[32:35], v[182:185], v[198:201], v[32:35]
	v_mfma_f32_16x16x32_bf16 v[20:23], v[172:175], v[206:209], v[20:23]
	v_mfma_f32_16x16x32_bf16 v[16:19], v[182:185], v[206:209], v[16:19]
	v_mfma_f32_16x16x32_bf16 v[4:7], v[172:175], v[214:217], v[4:7]
	v_mfma_f32_16x16x32_bf16 v[0:3], v[182:185], v[214:217], v[0:3]
	s_barrier
	s_add_i32 s45, s45, 2
	s_add_u32 s43, s43, 0x100
	s_addc_u32 s44, s44, 0
	s_cmp_gt_u32 s45, 41
	s_mov_b64 s[18:19], s[20:21]
	s_cbranch_scc0 .LBB0_1461
	s_and_b64 vcc, exec, s[14:15]
	s_cbranch_vccz .LBB0_1464
	s_barrier
